# baseline (speedup 1.0000x reference)
; __device__ __forceinline__ int opaque_tid() { int t = threadIdx.x; asm volatile("" : "+v"(t)); return t; }
; template <int G>
; __global__ void __launch_bounds__(256, 2) fwd_kernel(Params P) {
;     ...
;   unsigned bgen = 0;
;   bfu* sm = (bfu*)smraw;
;   const int tid = opaque_tid(), lane = tid & 63, wave = tid >> 6;
;   const int wr = wave >> 1, wc = wave & 1, c15 = lane & 15, g = lane >> 4;
;   Ptrs<G> w; w.b = P.ws;
;   __shared__ int s_xi[4];
;   {
;     int* xcnt = (int*)(P.ws + L::o_bar + 512);
;     const int myx = (int)(__builtin_amdgcn_s_getreg((3 << 11) | 20) & 0xFu);
;     if (tid == 0) { s_xi[1] = myx; s_xi[2] = (myx < 8) ? atomicAdd(xcnt + myx, 1) : 0; if (myx >= 8) atomicAdd(xcnt + 8, 1); }
_Z10fwd_kernelILi2EEv6Params:
	s_mov_b64 s[100:101], 0x4000
	s_load_dwordx8 s[4:11], s[0:1], 0x80
	s_load_dwordx4 s[16:19], s[0:1], 0xa0
	s_load_dword s52, s[0:1], 0xb0
	v_and_b32_e32 v174, 0x3ff, v0
	v_mov_b32_e32 v1, v174
	s_waitcnt lgkmcnt(0)
	v_writelane_b32 v252, s4, 0
	v_cmp_eq_u32_e64 s[54:55], 0, v1
	s_nop 0
	v_writelane_b32 v252, s5, 1
	v_writelane_b32 v252, s6, 2
	v_writelane_b32 v252, s7, 3
	v_writelane_b32 v252, s8, 4
	v_writelane_b32 v252, s9, 5
	v_writelane_b32 v252, s10, 6
	v_writelane_b32 v252, s11, 7
	s_add_u32 s4, s0, 0xb0
	s_addc_u32 s5, s1, 0
	v_writelane_b32 v252, s4, 8
	s_nop 1
	v_writelane_b32 v252, s5, 9
	s_getreg_b32 s4, hwreg(HW_REG_XCC_ID, 0, 4)
	s_and_saveexec_b64 s[12:13], s[54:55]
	s_cbranch_execz .LBB0_8
	s_and_b32 s8, s4, 15
	v_mov_b32_e32 v1, 0x12004
	v_mov_b32_e32 v2, s8
	ds_write_b32 v1, v2
	s_cmp_gt_u32 s8, 7
	v_mov_b32_e32 v1, 0
	s_cbranch_scc1 .LBB0_5
	s_mov_b64 s[6:7], exec
	v_mbcnt_lo_u32_b32 v1, s6, 0
	v_mbcnt_hi_u32_b32 v1, s7, v1
	v_cmp_eq_u32_e32 vcc, 0, v1
	s_and_saveexec_b64 s[4:5], vcc
	s_cbranch_execz .LBB0_4
	s_lshl_b32 s9, s8, 2
	s_bcnt1_i32_b64 s6, s[6:7]
	v_mov_b32_e32 v2, s9
	v_mov_b32_e32 v3, s6
	global_atomic_add v2, v2, v3, s[18:19] offset:1536 sc0

; __device__ __forceinline__ float bf2f(bfu h) { return __uint_as_float(((unsigned)h) << 16); }
; __device__ __forceinline__ float sigm(float x) { return 1.f / (1.f + __expf(-x)); }
;   __device__ __forceinline__ bfu* glu() const { return (bfu*)(b + L::o_glu); }
; template <int G>
; __device__ __forceinline__ void p2_conformer(const Params& P, const Ptrs<G>& w, int layer, int item, float* cv, int kslot) {
;     ...
;     for (int sr = 0; sr < 62; ++sr) {
;       const int s = t0 - 30 + sr;
;       float h0 = 0.f;
;       if (s >= 0) {
;         const bfu* gp = w.glu() + (seqbase + s) * 1024 + c;
;         h0 = bf2f(gp[0]) * sigm(bf2f(gp[512]));
;       }
; #pragma unroll
;       for (int tr = 0; tr < 32; ++tr) {
;         const int j = sr - tr;
;         if (j >= 0 && j <= 30) a[tr] += wj[j] * h0;
;       }
;     }
.LBB0_348:
	v_lshl_add_u64 v[4:5], v[4:5], 0, s[2:3]
	v_lshl_add_u64 v[100:101], v[4:5], 0, s[100:101]
	global_load_ushort v38, v[4:5], off offset:1024
	global_load_ushort v102, v[100:101], off offset:1024
	s_waitcnt vmcnt(2)
	v_fma_f32 v3, v68, v3, v7
	v_fmac_f32_e32 v3, v67, v8
	v_fma_f32 v8, v68, v8, v7
	v_fmac_f32_e32 v3, v66, v9
	v_fmac_f32_e32 v8, v67, v9
	v_fma_f32 v9, v68, v9, v7
	v_fmac_f32_e32 v3, v65, v10
	v_fmac_f32_e32 v8, v66, v10
	v_fmac_f32_e32 v9, v67, v10
	v_fma_f32 v10, v68, v10, v7
	v_fmac_f32_e32 v3, v64, v11
	v_fmac_f32_e32 v8, v65, v11
	v_fmac_f32_e32 v9, v66, v11
	v_fmac_f32_e32 v10, v67, v11
	v_fma_f32 v11, v68, v11, v7
	v_fmac_f32_e32 v3, v63, v12
	v_fmac_f32_e32 v8, v64, v12
	v_fmac_f32_e32 v9, v65, v12
	v_fmac_f32_e32 v10, v66, v12
	v_fmac_f32_e32 v11, v67, v12
	v_fma_f32 v12, v68, v12, v7
	v_fmac_f32_e32 v3, v62, v13
	v_fmac_f32_e32 v8, v63, v13
	v_fmac_f32_e32 v9, v64, v13
	v_fmac_f32_e32 v10, v65, v13
	v_fmac_f32_e32 v11, v66, v13
	v_fmac_f32_e32 v12, v67, v13
	v_fma_f32 v13, v68, v13, v7
	v_fmac_f32_e32 v3, v61, v14
	v_fmac_f32_e32 v8, v62, v14
	v_fmac_f32_e32 v9, v63, v14
	v_fmac_f32_e32 v10, v64, v14
	v_fmac_f32_e32 v11, v65, v14
	v_fmac_f32_e32 v12, v66, v14
	v_fmac_f32_e32 v13, v67, v14
	v_fma_f32 v14, v68, v14, v7
	v_fmac_f32_e32 v3, v60, v15
	v_fmac_f32_e32 v8, v61, v15
	v_fmac_f32_e32 v9, v62, v15
	v_fmac_f32_e32 v10, v63, v15
	v_fmac_f32_e32 v11, v64, v15
	v_fmac_f32_e32 v12, v65, v15
	v_fmac_f32_e32 v13, v66, v15
	v_fmac_f32_e32 v14, v67, v15
	v_fma_f32 v15, v68, v15, v7
	v_fmac_f32_e32 v3, v59, v17
	v_fmac_f32_e32 v8, v60, v17
	v_fmac_f32_e32 v9, v61, v17
	v_fmac_f32_e32 v10, v62, v17
	v_fmac_f32_e32 v11, v63, v17
	v_fmac_f32_e32 v12, v64, v17
	v_fmac_f32_e32 v13, v65, v17
	v_fmac_f32_e32 v14, v66, v17
	v_fmac_f32_e32 v15, v67, v17
	v_fma_f32 v17, v68, v17, v7
	v_fmac_f32_e32 v3, v58, v18
	v_fmac_f32_e32 v8, v59, v18
	v_fmac_f32_e32 v9, v60, v18
	v_fmac_f32_e32 v10, v61, v18
	v_fmac_f32_e32 v11, v62, v18
	v_fmac_f32_e32 v12, v63, v18
	v_fmac_f32_e32 v13, v64, v18
	v_fmac_f32_e32 v14, v65, v18
	v_fmac_f32_e32 v15, v66, v18
	v_fmac_f32_e32 v17, v67, v18
	v_fma_f32 v18, v68, v18, v7
	v_fmac_f32_e32 v3, v57, v19
	v_fmac_f32_e32 v8, v58, v19
	v_fmac_f32_e32 v9, v59, v19
	v_fmac_f32_e32 v10, v60, v19
	v_fmac_f32_e32 v11, v61, v19
	v_fmac_f32_e32 v12, v62, v19
	v_fmac_f32_e32 v13, v63, v19
	v_fmac_f32_e32 v14, v64, v19
	v_fmac_f32_e32 v15, v65, v19
	v_fmac_f32_e32 v17, v66, v19
	v_fmac_f32_e32 v18, v67, v19
	v_fma_f32 v19, v68, v19, v7
	v_fmac_f32_e32 v3, v56, v20
	s_waitcnt vmcnt(1)
	v_lshlrev_b32_e32 v38, 16, v38
	v_mul_f32_e32 v38, 0xbfb8aa3b, v38
	v_exp_f32_e32 v38, v38
	v_fmac_f32_e32 v8, v57, v20
	v_fmac_f32_e32 v9, v58, v20
	v_fmac_f32_e32 v10, v59, v20
	v_add_f32_e32 v38, 1.0, v38
	v_div_scale_f32 v69, s[72:73], v38, v38, 1.0
	v_rcp_f32_e32 v70, v69
	v_fmac_f32_e32 v11, v60, v20
	v_fmac_f32_e32 v12, v61, v20
	v_fmac_f32_e32 v13, v62, v20
	v_fma_f32 v71, -v69, v70, 1.0
	v_fmac_f32_e32 v70, v71, v70
	v_div_scale_f32 v71, vcc, 1.0, v38, 1.0
	v_mul_f32_e32 v72, v71, v70
	v_fma_f32 v73, -v69, v72, v71
	v_fmac_f32_e32 v72, v73, v70
	v_fma_f32 v69, -v69, v72, v71
	v_div_fmas_f32 v69, v69, v70, v72
	v_div_fixup_f32 v38, v69, v38, 1.0
	v_lshl_add_u64 v[100:101], v[4:5], 0, s[100:101]
	global_load_ushort v69, v[4:5], off
	global_load_ushort v102, v[100:101], off
	v_fmac_f32_e32 v14, v63, v20
	v_fmac_f32_e32 v15, v64, v20
	v_fmac_f32_e32 v17, v65, v20
	v_fmac_f32_e32 v18, v66, v20
	v_fmac_f32_e32 v19, v67, v20
	v_fma_f32 v20, v68, v20, v7
	v_fmac_f32_e32 v3, v55, v21
	v_fmac_f32_e32 v8, v56, v21
	v_fmac_f32_e32 v9, v57, v21
	v_fmac_f32_e32 v10, v58, v21
	v_fmac_f32_e32 v11, v59, v21
	v_fmac_f32_e32 v12, v60, v21
	v_fmac_f32_e32 v13, v61, v21
	v_fmac_f32_e32 v14, v62, v21
	v_fmac_f32_e32 v15, v63, v21
	v_fmac_f32_e32 v17, v64, v21
	v_fmac_f32_e32 v18, v65, v21
	v_fmac_f32_e32 v19, v66, v21
	v_fmac_f32_e32 v20, v67, v21
	v_fma_f32 v21, v68, v21, v7
	v_fmac_f32_e32 v3, v54, v22
	v_fmac_f32_e32 v8, v55, v22
	v_fmac_f32_e32 v9, v56, v22
	v_fmac_f32_e32 v10, v57, v22
	v_fmac_f32_e32 v11, v58, v22
	v_fmac_f32_e32 v12, v59, v22
	v_fmac_f32_e32 v13, v60, v22
	v_fmac_f32_e32 v14, v61, v22
	v_fmac_f32_e32 v15, v62, v22
	v_fmac_f32_e32 v17, v63, v22
	v_fmac_f32_e32 v18, v64, v22
	v_fmac_f32_e32 v19, v65, v22
	v_fmac_f32_e32 v20, v66, v22
	v_fmac_f32_e32 v21, v67, v22
	v_fma_f32 v22, v68, v22, v7
	v_fmac_f32_e32 v3, v53, v23
	v_fmac_f32_e32 v8, v54, v23
	v_fmac_f32_e32 v9, v55, v23
	v_fmac_f32_e32 v10, v56, v23
	v_fmac_f32_e32 v11, v57, v23
	v_fmac_f32_e32 v12, v58, v23
	v_fmac_f32_e32 v13, v59, v23
	v_fmac_f32_e32 v14, v60, v23
	v_fmac_f32_e32 v15, v61, v23
	v_fmac_f32_e32 v17, v62, v23
	v_fmac_f32_e32 v18, v63, v23
	v_fmac_f32_e32 v19, v64, v23
	v_fmac_f32_e32 v20, v65, v23
	v_fmac_f32_e32 v21, v66, v23
	v_fmac_f32_e32 v22, v67, v23
	v_fma_f32 v23, v68, v23, v7
	v_fmac_f32_e32 v3, v52, v24
	v_fmac_f32_e32 v8, v53, v24
	v_fmac_f32_e32 v9, v54, v24
	v_fmac_f32_e32 v10, v55, v24
	v_fmac_f32_e32 v11, v56, v24
	v_fmac_f32_e32 v12, v57, v24
	v_fmac_f32_e32 v13, v58, v24
	v_fmac_f32_e32 v14, v59, v24
	v_fmac_f32_e32 v15, v60, v24
	v_fmac_f32_e32 v17, v61, v24
	v_fmac_f32_e32 v18, v62, v24
	v_fmac_f32_e32 v19, v63, v24
	v_fmac_f32_e32 v20, v64, v24
	v_fmac_f32_e32 v21, v65, v24
	v_fmac_f32_e32 v22, v66, v24
	v_fmac_f32_e32 v23, v67, v24
	v_fma_f32 v24, v68, v24, v7
	v_fmac_f32_e32 v3, v51, v25
	v_fmac_f32_e32 v8, v52, v25
	v_fmac_f32_e32 v9, v53, v25
	v_fmac_f32_e32 v10, v54, v25
	v_fmac_f32_e32 v11, v55, v25
	v_fmac_f32_e32 v12, v56, v25
	v_fmac_f32_e32 v13, v57, v25
	v_fmac_f32_e32 v14, v58, v25
	v_fmac_f32_e32 v15, v59, v25
	v_fmac_f32_e32 v17, v60, v25
	v_fmac_f32_e32 v18, v61, v25
	s_waitcnt vmcnt(1)
; __device__ __forceinline__ float bf2f(bfu h) { return __uint_as_float(((unsigned)h) << 16); }
; __device__ __forceinline__ float sigm(float x) { return 1.f / (1.f + __expf(-x)); }
;   __device__ __forceinline__ bfu* glu() const { return (bfu*)(b + L::o_glu); }
; template <int G>
; __device__ __forceinline__ void p2_conformer(const Params& P, const Ptrs<G>& w, int layer, int item, float* cv, int kslot) {
;     ...
;     for (int sr = 0; sr < 62; ++sr) {
;       const int s = t0 - 30 + sr;
;       float h0 = 0.f;
;       if (s >= 0) {
;         const bfu* gp = w.glu() + (seqbase + s) * 1024 + c;
;         h0 = bf2f(gp[0]) * sigm(bf2f(gp[512]));
;       }
; #pragma unroll
;       for (int tr = 0; tr < 32; ++tr) {
;         const int j = sr - tr;
;         if (j >= 0 && j <= 30) a[tr] += wj[j] * h0;
;       }
;     }
	v_lshlrev_b32_e32 v69, 16, v69
	v_mul_f32_e32 v38, v38, v69
	v_lshl_add_u64 v[100:101], v[4:5], 0, s[100:101]
	global_load_ushort v69, v[4:5], off offset:3072
	global_load_ushort v102, v[100:101], off offset:3072
	v_fmac_f32_e32 v19, v62, v25
	v_fmac_f32_e32 v20, v63, v25
	v_fmac_f32_e32 v21, v64, v25
	v_fmac_f32_e32 v22, v65, v25
	v_fmac_f32_e32 v23, v66, v25
	v_fmac_f32_e32 v24, v67, v25
	v_fma_f32 v25, v68, v25, v7
	v_fmac_f32_e32 v3, v50, v26
	v_fmac_f32_e32 v8, v51, v26
	v_fmac_f32_e32 v9, v52, v26
	v_fmac_f32_e32 v10, v53, v26
	v_fmac_f32_e32 v11, v54, v26
	v_fmac_f32_e32 v12, v55, v26
	v_fmac_f32_e32 v13, v56, v26
	v_fmac_f32_e32 v14, v57, v26
	v_fmac_f32_e32 v15, v58, v26
	v_fmac_f32_e32 v17, v59, v26
	v_fmac_f32_e32 v18, v60, v26
	v_fmac_f32_e32 v19, v61, v26
	v_fmac_f32_e32 v20, v62, v26
	v_fmac_f32_e32 v21, v63, v26
	v_fmac_f32_e32 v22, v64, v26
	v_fmac_f32_e32 v23, v65, v26
	v_fmac_f32_e32 v24, v66, v26
	v_fmac_f32_e32 v25, v67, v26
	v_fma_f32 v26, v68, v26, v7
	v_fmac_f32_e32 v3, v49, v27
	v_fmac_f32_e32 v8, v50, v27
	v_fmac_f32_e32 v9, v51, v27
	v_fmac_f32_e32 v10, v52, v27
	v_fmac_f32_e32 v11, v53, v27
	v_fmac_f32_e32 v12, v54, v27
	v_fmac_f32_e32 v13, v55, v27
	v_fmac_f32_e32 v14, v56, v27
	v_fmac_f32_e32 v15, v57, v27
	v_fmac_f32_e32 v17, v58, v27
	v_fmac_f32_e32 v18, v59, v27
	v_fmac_f32_e32 v19, v60, v27
	v_fmac_f32_e32 v20, v61, v27
	v_fmac_f32_e32 v21, v62, v27
	v_fmac_f32_e32 v22, v63, v27
	v_fmac_f32_e32 v23, v64, v27
	v_fmac_f32_e32 v24, v65, v27
	v_fmac_f32_e32 v25, v66, v27
	v_fmac_f32_e32 v26, v67, v27
	v_fma_f32 v27, v68, v27, v7
	v_fmac_f32_e32 v3, v48, v28
	v_fmac_f32_e32 v8, v49, v28
	v_fmac_f32_e32 v9, v50, v28
	v_fmac_f32_e32 v10, v51, v28
	v_fmac_f32_e32 v11, v52, v28
	v_fmac_f32_e32 v12, v53, v28
	v_fmac_f32_e32 v13, v54, v28
	v_fmac_f32_e32 v14, v55, v28
	v_fmac_f32_e32 v15, v56, v28
	v_fmac_f32_e32 v17, v57, v28
	v_fmac_f32_e32 v18, v58, v28
	v_fmac_f32_e32 v19, v59, v28
	v_fmac_f32_e32 v20, v60, v28
	v_fmac_f32_e32 v21, v61, v28
	v_fmac_f32_e32 v22, v62, v28
	v_fmac_f32_e32 v23, v63, v28
	v_fmac_f32_e32 v24, v64, v28
	v_fmac_f32_e32 v25, v65, v28
	v_fmac_f32_e32 v26, v66, v28
	v_fmac_f32_e32 v27, v67, v28
	v_fma_f32 v28, v68, v28, v7
	v_fmac_f32_e32 v3, v46, v29
	v_fmac_f32_e32 v8, v48, v29
	v_fmac_f32_e32 v9, v49, v29
	v_fmac_f32_e32 v10, v50, v29
	v_fmac_f32_e32 v11, v51, v29
	v_fmac_f32_e32 v12, v52, v29
	v_fmac_f32_e32 v13, v53, v29
	v_fmac_f32_e32 v14, v54, v29
	v_fmac_f32_e32 v15, v55, v29
	v_fmac_f32_e32 v17, v56, v29
	v_fmac_f32_e32 v18, v57, v29
	v_fmac_f32_e32 v19, v58, v29
	s_waitcnt vmcnt(1)
	v_lshlrev_b32_e32 v69, 16, v69
	v_mul_f32_e32 v69, 0xbfb8aa3b, v69
	v_exp_f32_e32 v69, v69
	v_fmac_f32_e32 v20, v59, v29
	v_fmac_f32_e32 v21, v60, v29
	v_fmac_f32_e32 v22, v61, v29
	v_add_f32_e32 v69, 1.0, v69
	v_div_scale_f32 v70, s[72:73], v69, v69, 1.0
	v_rcp_f32_e32 v71, v70
	v_fmac_f32_e32 v23, v62, v29
	v_fmac_f32_e32 v24, v63, v29
	v_fmac_f32_e32 v25, v64, v29
	v_fma_f32 v72, -v70, v71, 1.0
	v_fmac_f32_e32 v71, v72, v71
	v_div_scale_f32 v72, vcc, 1.0, v69, 1.0
	v_mul_f32_e32 v73, v72, v71
	v_fma_f32 v74, -v70, v73, v72
	v_fmac_f32_e32 v73, v74, v71
	v_fma_f32 v70, -v70, v73, v72
	v_div_fmas_f32 v70, v70, v71, v73
	v_div_fixup_f32 v69, v70, v69, 1.0
	v_lshl_add_u64 v[100:101], v[4:5], 0, s[100:101]
	global_load_ushort v70, v[4:5], off offset:2048
	global_load_ushort v102, v[100:101], off offset:2048
	v_fmac_f32_e32 v26, v65, v29
	v_fmac_f32_e32 v27, v66, v29
	v_fmac_f32_e32 v28, v67, v29
	v_fma_f32 v29, v68, v29, v7
	v_fmac_f32_e32 v3, v47, v30
	v_fmac_f32_e32 v8, v46, v30
	v_fmac_f32_e32 v9, v48, v30
	v_fmac_f32_e32 v10, v49, v30
	v_fmac_f32_e32 v11, v50, v30
	v_fmac_f32_e32 v12, v51, v30
	v_fmac_f32_e32 v13, v52, v30
	v_fmac_f32_e32 v14, v53, v30
	v_fmac_f32_e32 v15, v54, v30
	v_fmac_f32_e32 v17, v55, v30
	v_fmac_f32_e32 v18, v56, v30
	v_fmac_f32_e32 v19, v57, v30
	v_fmac_f32_e32 v20, v58, v30
	v_fmac_f32_e32 v21, v59, v30
	v_fmac_f32_e32 v22, v60, v30
	v_fmac_f32_e32 v23, v61, v30
	v_fmac_f32_e32 v24, v62, v30
	v_fmac_f32_e32 v25, v63, v30
	v_fmac_f32_e32 v26, v64, v30
	v_fmac_f32_e32 v27, v65, v30
	v_fmac_f32_e32 v28, v66, v30
	v_fmac_f32_e32 v29, v67, v30
	v_fma_f32 v30, v68, v30, v7
	v_fmac_f32_e32 v3, v45, v31
	v_fmac_f32_e32 v8, v47, v31
	v_fmac_f32_e32 v9, v46, v31
	v_fmac_f32_e32 v10, v48, v31
	v_fmac_f32_e32 v11, v49, v31
	v_fmac_f32_e32 v12, v50, v31
	v_fmac_f32_e32 v13, v51, v31
	v_fmac_f32_e32 v14, v52, v31
	v_fmac_f32_e32 v15, v53, v31
	v_fmac_f32_e32 v17, v54, v31
	v_fmac_f32_e32 v18, v55, v31
	v_fmac_f32_e32 v19, v56, v31
	v_fmac_f32_e32 v20, v57, v31
	v_fmac_f32_e32 v21, v58, v31
	v_fmac_f32_e32 v22, v59, v31
	v_fmac_f32_e32 v23, v60, v31
	v_fmac_f32_e32 v24, v61, v31
	v_fmac_f32_e32 v25, v62, v31
	v_fmac_f32_e32 v26, v63, v31
	v_fmac_f32_e32 v27, v64, v31
	v_fmac_f32_e32 v28, v65, v31
	v_fmac_f32_e32 v29, v66, v31
	v_fmac_f32_e32 v30, v67, v31
	v_fma_f32 v31, v68, v31, v7
	v_fmac_f32_e32 v3, v44, v32
	v_fmac_f32_e32 v8, v45, v32
	v_fmac_f32_e32 v9, v47, v32
	v_fmac_f32_e32 v10, v46, v32
	v_fmac_f32_e32 v11, v48, v32
	v_fmac_f32_e32 v12, v49, v32
	v_fmac_f32_e32 v13, v50, v32
	v_fmac_f32_e32 v14, v51, v32
	v_fmac_f32_e32 v15, v52, v32
	v_fmac_f32_e32 v17, v53, v32
	v_fmac_f32_e32 v18, v54, v32
	v_fmac_f32_e32 v19, v55, v32
	v_fmac_f32_e32 v20, v56, v32
	v_fmac_f32_e32 v21, v57, v32
	v_fmac_f32_e32 v22, v58, v32
	v_fmac_f32_e32 v23, v59, v32
	v_fmac_f32_e32 v24, v60, v32
	v_fmac_f32_e32 v25, v61, v32
	v_fmac_f32_e32 v26, v62, v32
	v_fmac_f32_e32 v27, v63, v32
	v_fmac_f32_e32 v28, v64, v32
	v_fmac_f32_e32 v29, v65, v32
	v_fmac_f32_e32 v30, v66, v32
	v_fmac_f32_e32 v31, v67, v32
; __device__ __forceinline__ float bf2f(bfu h) { return __uint_as_float(((unsigned)h) << 16); }
; __device__ __forceinline__ float sigm(float x) { return 1.f / (1.f + __expf(-x)); }
;   __device__ __forceinline__ bfu* glu() const { return (bfu*)(b + L::o_glu); }
; template <int G>
; __device__ __forceinline__ void p2_conformer(const Params& P, const Ptrs<G>& w, int layer, int item, float* cv, int kslot) {
;     ...
;     for (int sr = 0; sr < 62; ++sr) {
;       const int s = t0 - 30 + sr;
;       float h0 = 0.f;
;       if (s >= 0) {
;         const bfu* gp = w.glu() + (seqbase + s) * 1024 + c;
;         h0 = bf2f(gp[0]) * sigm(bf2f(gp[512]));
;       }
; #pragma unroll
;       for (int tr = 0; tr < 32; ++tr) {
;         const int j = sr - tr;
;         if (j >= 0 && j <= 30) a[tr] += wj[j] * h0;
;       }
;     }
	v_fma_f32 v32, v68, v32, v7
	v_fmac_f32_e32 v3, v43, v33
	v_fmac_f32_e32 v8, v44, v33
	v_fmac_f32_e32 v9, v45, v33
	v_fmac_f32_e32 v10, v47, v33
	v_fmac_f32_e32 v11, v46, v33
	v_fmac_f32_e32 v12, v48, v33
	v_fmac_f32_e32 v13, v49, v33
	v_fmac_f32_e32 v14, v50, v33
	v_fmac_f32_e32 v15, v51, v33
	v_fmac_f32_e32 v17, v52, v33
	v_fmac_f32_e32 v18, v53, v33
	v_fmac_f32_e32 v19, v54, v33
	v_fmac_f32_e32 v20, v55, v33
	v_fmac_f32_e32 v21, v56, v33
	v_fmac_f32_e32 v22, v57, v33
	v_fmac_f32_e32 v23, v58, v33
	v_fmac_f32_e32 v24, v59, v33
	v_fmac_f32_e32 v25, v60, v33
	v_fmac_f32_e32 v26, v61, v33
	v_fmac_f32_e32 v27, v62, v33
	v_fmac_f32_e32 v28, v63, v33
	v_fmac_f32_e32 v29, v64, v33
	v_fmac_f32_e32 v30, v65, v33
	v_fmac_f32_e32 v31, v66, v33
	v_fmac_f32_e32 v32, v67, v33
	v_fma_f32 v33, v68, v33, v7
	v_fmac_f32_e32 v3, v42, v34
	v_fmac_f32_e32 v8, v43, v34
	v_fmac_f32_e32 v9, v44, v34
	v_fmac_f32_e32 v10, v45, v34
	v_fmac_f32_e32 v11, v47, v34
	v_fmac_f32_e32 v12, v46, v34
	v_fmac_f32_e32 v13, v48, v34
	v_fmac_f32_e32 v14, v49, v34
	v_fmac_f32_e32 v15, v50, v34
	v_fmac_f32_e32 v17, v51, v34
	v_fmac_f32_e32 v18, v52, v34
	v_fmac_f32_e32 v19, v53, v34
	v_fmac_f32_e32 v20, v54, v34
	v_fmac_f32_e32 v21, v55, v34
	v_fmac_f32_e32 v22, v56, v34
	v_fmac_f32_e32 v23, v57, v34
	v_fmac_f32_e32 v24, v58, v34
	v_fmac_f32_e32 v25, v59, v34
	v_fmac_f32_e32 v26, v60, v34
	v_fmac_f32_e32 v27, v61, v34
	v_fmac_f32_e32 v28, v62, v34
	v_fmac_f32_e32 v29, v63, v34
	v_fmac_f32_e32 v30, v64, v34
	v_fmac_f32_e32 v31, v65, v34
	v_fmac_f32_e32 v32, v66, v34
	v_fmac_f32_e32 v33, v67, v34
	v_fma_f32 v34, v68, v34, v7
	v_fmac_f32_e32 v3, v41, v35
	v_fmac_f32_e32 v8, v42, v35
	v_fmac_f32_e32 v9, v43, v35
	v_fmac_f32_e32 v10, v44, v35
	v_fmac_f32_e32 v11, v45, v35
	v_fmac_f32_e32 v12, v47, v35
	v_fmac_f32_e32 v13, v46, v35
	v_fmac_f32_e32 v14, v48, v35
	v_fmac_f32_e32 v15, v49, v35
	v_fmac_f32_e32 v17, v50, v35
	v_fmac_f32_e32 v18, v51, v35
	v_fmac_f32_e32 v19, v52, v35
	v_fmac_f32_e32 v20, v53, v35
	v_fmac_f32_e32 v21, v54, v35
	v_fmac_f32_e32 v22, v55, v35
	v_fmac_f32_e32 v23, v56, v35
	v_fmac_f32_e32 v24, v57, v35
	v_fmac_f32_e32 v25, v58, v35
	v_fmac_f32_e32 v26, v59, v35
	v_fmac_f32_e32 v27, v60, v35
	v_fmac_f32_e32 v28, v61, v35
	v_fmac_f32_e32 v29, v62, v35
	v_fmac_f32_e32 v30, v63, v35
	v_fmac_f32_e32 v31, v64, v35
	v_fmac_f32_e32 v32, v65, v35
	v_fmac_f32_e32 v33, v66, v35
	v_fmac_f32_e32 v34, v67, v35
	v_fma_f32 v35, v68, v35, v7
	v_fmac_f32_e32 v3, v40, v36
	v_fmac_f32_e32 v8, v41, v36
	v_fmac_f32_e32 v9, v42, v36
	v_fmac_f32_e32 v10, v43, v36
	v_fmac_f32_e32 v11, v44, v36
	v_fmac_f32_e32 v12, v45, v36
	v_fmac_f32_e32 v13, v47, v36
	v_fmac_f32_e32 v14, v46, v36
	v_fmac_f32_e32 v15, v48, v36
	v_fmac_f32_e32 v17, v49, v36
	v_fmac_f32_e32 v18, v50, v36
	v_fmac_f32_e32 v19, v51, v36
	v_fmac_f32_e32 v20, v52, v36
	v_fmac_f32_e32 v21, v53, v36
	v_fmac_f32_e32 v22, v54, v36
	v_fmac_f32_e32 v23, v55, v36
	v_fmac_f32_e32 v24, v56, v36
	v_fmac_f32_e32 v25, v57, v36
	v_fmac_f32_e32 v26, v58, v36
	v_fmac_f32_e32 v27, v59, v36
	v_fmac_f32_e32 v28, v60, v36
	v_fmac_f32_e32 v29, v61, v36
	v_fmac_f32_e32 v30, v62, v36
	v_fmac_f32_e32 v31, v63, v36
	v_fmac_f32_e32 v32, v64, v36
	v_fmac_f32_e32 v33, v65, v36
	v_fmac_f32_e32 v34, v66, v36
	v_fmac_f32_e32 v35, v67, v36
	v_fma_f32 v36, v68, v36, v7
	s_waitcnt vmcnt(1)
	v_lshlrev_b32_e32 v70, 16, v70
	v_fmac_f32_e32 v3, v39, v37
	v_fmac_f32_e32 v8, v40, v37
	v_fmac_f32_e32 v9, v41, v37
	v_fmac_f32_e32 v10, v42, v37
	v_fmac_f32_e32 v11, v43, v37
	v_fmac_f32_e32 v12, v44, v37
	v_fmac_f32_e32 v13, v45, v37
	v_fmac_f32_e32 v14, v47, v37
	v_fmac_f32_e32 v15, v46, v37
	v_fmac_f32_e32 v17, v48, v37
	v_fmac_f32_e32 v18, v49, v37
	v_fmac_f32_e32 v19, v50, v37
	v_fmac_f32_e32 v20, v51, v37
	v_fmac_f32_e32 v21, v52, v37
	v_fmac_f32_e32 v22, v53, v37
	v_fmac_f32_e32 v23, v54, v37
	v_fmac_f32_e32 v24, v55, v37
	v_fmac_f32_e32 v25, v56, v37
	v_fmac_f32_e32 v26, v57, v37
	v_fmac_f32_e32 v27, v58, v37
	v_fmac_f32_e32 v28, v59, v37
	v_fmac_f32_e32 v29, v60, v37
	v_fmac_f32_e32 v30, v61, v37
	v_fmac_f32_e32 v31, v62, v37
	v_fmac_f32_e32 v32, v63, v37
	v_fmac_f32_e32 v33, v64, v37
	v_fmac_f32_e32 v34, v65, v37
	v_fmac_f32_e32 v35, v66, v37
	v_fmac_f32_e32 v36, v67, v37
	v_fma_f32 v37, v68, v37, v7
	v_mul_f32_e32 v69, v69, v70
	s_movk_i32 s17, 0x1000
	v_fmac_f32_e32 v3, v6, v38
	v_fmac_f32_e32 v8, v39, v38
	v_fmac_f32_e32 v9, v40, v38
	v_fmac_f32_e32 v10, v41, v38
	v_fmac_f32_e32 v11, v42, v38
	v_fmac_f32_e32 v12, v43, v38
	v_fmac_f32_e32 v13, v44, v38
	v_fmac_f32_e32 v14, v45, v38
	v_fmac_f32_e32 v15, v47, v38
	v_fmac_f32_e32 v17, v46, v38
	v_fmac_f32_e32 v18, v48, v38
	v_fmac_f32_e32 v19, v49, v38
	v_fmac_f32_e32 v20, v50, v38
	v_fmac_f32_e32 v21, v51, v38
	v_fmac_f32_e32 v22, v52, v38
	v_fmac_f32_e32 v23, v53, v38
	v_fmac_f32_e32 v24, v54, v38
	v_fmac_f32_e32 v25, v55, v38
	v_fmac_f32_e32 v26, v56, v38
	v_fmac_f32_e32 v27, v57, v38
	v_fmac_f32_e32 v28, v58, v38
	v_fmac_f32_e32 v29, v59, v38
	v_fmac_f32_e32 v30, v60, v38
	v_fmac_f32_e32 v31, v61, v38
	v_fmac_f32_e32 v32, v62, v38
	v_fmac_f32_e32 v33, v63, v38
	v_fmac_f32_e32 v34, v64, v38
	v_fmac_f32_e32 v35, v65, v38
	v_fmac_f32_e32 v36, v66, v38
	v_fmac_f32_e32 v37, v67, v38
	v_fma_f32 v38, v68, v38, v7
	v_fmac_f32_e32 v7, v68, v69
	v_add_co_u32_e32 v68, vcc, s17, v4
	v_fmac_f32_e32 v8, v6, v69
	v_fmac_f32_e32 v9, v39, v69
	v_fmac_f32_e32 v10, v40, v69
	v_fmac_f32_e32 v11, v41, v69
	v_fmac_f32_e32 v12, v42, v69
	v_fmac_f32_e32 v13, v43, v69
	v_fmac_f32_e32 v14, v44, v69
	v_fmac_f32_e32 v15, v45, v69
	v_fmac_f32_e32 v17, v47, v69
	v_fmac_f32_e32 v18, v46, v69
	v_fmac_f32_e32 v19, v48, v69
	v_fmac_f32_e32 v20, v49, v69
	v_fmac_f32_e32 v21, v50, v69
	v_fmac_f32_e32 v22, v51, v69
	v_fmac_f32_e32 v23, v52, v69
	v_fmac_f32_e32 v24, v53, v69
	v_fmac_f32_e32 v25, v54, v69
	v_fmac_f32_e32 v26, v55, v69
	v_fmac_f32_e32 v27, v56, v69
	v_fmac_f32_e32 v28, v57, v69
	v_fmac_f32_e32 v29, v58, v69
	v_fmac_f32_e32 v30, v59, v69
	v_fmac_f32_e32 v31, v60, v69
	v_fmac_f32_e32 v32, v61, v69
	v_fmac_f32_e32 v33, v62, v69
	v_fmac_f32_e32 v34, v63, v69
	v_fmac_f32_e32 v35, v64, v69
	v_fmac_f32_e32 v36, v65, v69
	v_fmac_f32_e32 v37, v66, v69
	v_fmac_f32_e32 v38, v67, v69
	v_addc_co_u32_e32 v69, vcc, 0, v5, vcc
	v_lshl_add_u64 v[100:101], v[68:69], 0, s[100:101]
	global_load_ushort v70, v[68:69], off offset:1024
	global_load_ushort v102, v[100:101], off offset:1024
	s_movk_i32 s17, 0x2000
	s_xor_b64 s[10:11], s[92:93], -1
	s_mov_b32 s92, 0xf000
	v_lshlrev_b32_e32 v2, 2, v2
	s_waitcnt vmcnt(1)
; __device__ __forceinline__ float bf2f(bfu h) { return __uint_as_float(((unsigned)h) << 16); }
; __device__ __forceinline__ float sigm(float x) { return 1.f / (1.f + __expf(-x)); }
;   __device__ __forceinline__ bfu* glu() const { return (bfu*)(b + L::o_glu); }
; template <int G>
; __device__ __forceinline__ void p2_conformer(const Params& P, const Ptrs<G>& w, int layer, int item, float* cv, int kslot) {
;     ...
;     for (int sr = 0; sr < 62; ++sr) {
;       const int s = t0 - 30 + sr;
;       float h0 = 0.f;
;       if (s >= 0) {
;         const bfu* gp = w.glu() + (seqbase + s) * 1024 + c;
;         h0 = bf2f(gp[0]) * sigm(bf2f(gp[512]));
;       }
; #pragma unroll
;       for (int tr = 0; tr < 32; ++tr) {
;         const int j = sr - tr;
;         if (j >= 0 && j <= 30) a[tr] += wj[j] * h0;
;       }
;     }
	v_lshlrev_b32_e32 v70, 16, v70
	v_mul_f32_e32 v70, 0xbfb8aa3b, v70
	v_exp_f32_e32 v70, v70
	s_nop 0
	v_add_f32_e32 v70, 1.0, v70
	v_div_scale_f32 v71, s[72:73], v70, v70, 1.0
	v_rcp_f32_e32 v72, v71
	s_nop 0
	v_fma_f32 v73, -v71, v72, 1.0
	v_fmac_f32_e32 v72, v73, v72
	v_div_scale_f32 v73, vcc, 1.0, v70, 1.0
	v_mul_f32_e32 v74, v73, v72
	v_fma_f32 v75, -v71, v74, v73
	v_fmac_f32_e32 v74, v75, v72
	v_fma_f32 v71, -v71, v74, v73
	v_div_fmas_f32 v71, v71, v72, v74
	v_div_fixup_f32 v72, v71, v70, 1.0
	v_add_co_u32_e32 v70, vcc, s17, v4
	s_movk_i32 s17, 0x3000
	s_nop 0
	v_addc_co_u32_e32 v71, vcc, 0, v5, vcc
	v_lshl_add_u64 v[100:101], v[70:71], 0, s[100:101]
	global_load_ushort v73, v[70:71], off offset:-4096
	global_load_ushort v102, v[100:101], off offset:-4096
	s_waitcnt vmcnt(1)
	v_lshlrev_b32_e32 v73, 16, v73
	v_mul_f32_e32 v72, v72, v73
	v_fmac_f32_e32 v7, v67, v72
	v_lshl_add_u64 v[100:101], v[68:69], 0, s[100:101]
	global_load_ushort v67, v[68:69], off offset:3072
	global_load_ushort v102, v[100:101], off offset:3072
	v_fmac_f32_e32 v9, v6, v72
	v_lshl_add_u64 v[100:101], v[68:69], 0, s[100:101]
	global_load_ushort v68, v[68:69], off offset:2048
	global_load_ushort v102, v[100:101], off offset:2048
	v_fmac_f32_e32 v10, v39, v72
	v_fmac_f32_e32 v11, v40, v72
	v_fmac_f32_e32 v12, v41, v72
	v_fmac_f32_e32 v13, v42, v72
	v_fmac_f32_e32 v14, v43, v72
	v_fmac_f32_e32 v15, v44, v72
	v_fmac_f32_e32 v17, v45, v72
	v_fmac_f32_e32 v18, v47, v72
	v_fmac_f32_e32 v19, v46, v72
	v_fmac_f32_e32 v20, v48, v72
	v_fmac_f32_e32 v21, v49, v72
	v_fmac_f32_e32 v22, v50, v72
	v_fmac_f32_e32 v23, v51, v72
	v_fmac_f32_e32 v24, v52, v72
	v_fmac_f32_e32 v25, v53, v72
	v_fmac_f32_e32 v26, v54, v72
	v_fmac_f32_e32 v27, v55, v72
	v_fmac_f32_e32 v28, v56, v72
	v_fmac_f32_e32 v29, v57, v72
	v_fmac_f32_e32 v30, v58, v72
	v_fmac_f32_e32 v31, v59, v72
	v_fmac_f32_e32 v32, v60, v72
	v_fmac_f32_e32 v33, v61, v72
	v_fmac_f32_e32 v34, v62, v72
	v_fmac_f32_e32 v35, v63, v72
	v_fmac_f32_e32 v36, v64, v72
	v_fmac_f32_e32 v37, v65, v72
	v_fmac_f32_e32 v38, v66, v72
	s_waitcnt vmcnt(3)
	v_lshlrev_b32_e32 v67, 16, v67
	v_mul_f32_e32 v67, 0xbfb8aa3b, v67
	v_exp_f32_e32 v67, v67
	s_waitcnt vmcnt(1)
	v_lshlrev_b32_e32 v68, 16, v68
	v_add_f32_e32 v67, 1.0, v67
	v_div_scale_f32 v72, s[72:73], v67, v67, 1.0
	v_rcp_f32_e32 v73, v72
	s_nop 0
	v_fma_f32 v74, -v72, v73, 1.0
	v_fmac_f32_e32 v73, v74, v73
	v_div_scale_f32 v74, vcc, 1.0, v67, 1.0
	v_mul_f32_e32 v75, v74, v73
	v_fma_f32 v76, -v72, v75, v74
	v_fmac_f32_e32 v75, v76, v73
	v_fma_f32 v72, -v72, v75, v74
	v_div_fmas_f32 v72, v72, v73, v75
	v_div_fixup_f32 v67, v72, v67, 1.0
	v_mul_f32_e32 v67, v67, v68
	v_fmac_f32_e32 v7, v66, v67
	v_lshl_add_u64 v[100:101], v[70:71], 0, s[100:101]
	global_load_ushort v66, v[70:71], off offset:1024
	global_load_ushort v102, v[100:101], off offset:1024
	v_fmac_f32_e32 v10, v6, v67
	v_fmac_f32_e32 v11, v39, v67
	v_fmac_f32_e32 v12, v40, v67
	v_fmac_f32_e32 v13, v41, v67
	v_fmac_f32_e32 v14, v42, v67
	v_fmac_f32_e32 v15, v43, v67
	v_fmac_f32_e32 v17, v44, v67
	v_fmac_f32_e32 v18, v45, v67
	v_fmac_f32_e32 v19, v47, v67
	v_fmac_f32_e32 v20, v46, v67
	v_fmac_f32_e32 v21, v48, v67
	v_fmac_f32_e32 v22, v49, v67
	v_fmac_f32_e32 v23, v50, v67
	v_fmac_f32_e32 v24, v51, v67
	v_fmac_f32_e32 v25, v52, v67
	v_fmac_f32_e32 v26, v53, v67
	v_fmac_f32_e32 v27, v54, v67
	v_fmac_f32_e32 v28, v55, v67
	v_fmac_f32_e32 v29, v56, v67
	v_fmac_f32_e32 v30, v57, v67
	v_fmac_f32_e32 v31, v58, v67
	v_fmac_f32_e32 v32, v59, v67
	v_fmac_f32_e32 v33, v60, v67
	v_fmac_f32_e32 v34, v61, v67
	v_fmac_f32_e32 v35, v62, v67
	v_fmac_f32_e32 v36, v63, v67
	v_fmac_f32_e32 v37, v64, v67
	v_fmac_f32_e32 v38, v65, v67
	s_waitcnt vmcnt(1)
	v_lshlrev_b32_e32 v66, 16, v66
	v_mul_f32_e32 v66, 0xbfb8aa3b, v66
	v_exp_f32_e32 v66, v66
	s_nop 0
	v_add_f32_e32 v66, 1.0, v66
	v_div_scale_f32 v67, s[72:73], v66, v66, 1.0
	v_rcp_f32_e32 v68, v67
	s_nop 0
	v_fma_f32 v69, -v67, v68, 1.0
	v_fmac_f32_e32 v68, v69, v68
	v_div_scale_f32 v69, vcc, 1.0, v66, 1.0
	v_mul_f32_e32 v72, v69, v68
	v_fma_f32 v73, -v67, v72, v69
	v_fmac_f32_e32 v72, v73, v68
	v_fma_f32 v67, -v67, v72, v69
	v_div_fmas_f32 v67, v67, v68, v72
	v_div_fixup_f32 v66, v67, v66, 1.0
	v_lshl_add_u64 v[100:101], v[70:71], 0, s[100:101]
	global_load_ushort v67, v[70:71], off
	global_load_ushort v102, v[100:101], off
	s_waitcnt vmcnt(1)
	v_lshlrev_b32_e32 v67, 16, v67
	v_mul_f32_e32 v66, v66, v67
	v_fmac_f32_e32 v7, v65, v66
	v_lshl_add_u64 v[100:101], v[70:71], 0, s[100:101]
	global_load_ushort v65, v[70:71], off offset:3072
	global_load_ushort v102, v[100:101], off offset:3072
	v_fmac_f32_e32 v11, v6, v66
	v_fmac_f32_e32 v12, v39, v66
	v_fmac_f32_e32 v13, v40, v66
	v_fmac_f32_e32 v14, v41, v66
	v_fmac_f32_e32 v15, v42, v66
	v_fmac_f32_e32 v17, v43, v66
	v_fmac_f32_e32 v18, v44, v66
	v_fmac_f32_e32 v19, v45, v66
	v_fmac_f32_e32 v20, v47, v66
	v_fmac_f32_e32 v21, v46, v66
	v_fmac_f32_e32 v22, v48, v66
	v_fmac_f32_e32 v23, v49, v66
	v_fmac_f32_e32 v24, v50, v66
	v_fmac_f32_e32 v25, v51, v66
	v_fmac_f32_e32 v26, v52, v66
	v_fmac_f32_e32 v27, v53, v66
	v_fmac_f32_e32 v28, v54, v66
	v_fmac_f32_e32 v29, v55, v66
	v_fmac_f32_e32 v30, v56, v66
	v_fmac_f32_e32 v31, v57, v66
	v_fmac_f32_e32 v32, v58, v66
	v_fmac_f32_e32 v33, v59, v66
	v_fmac_f32_e32 v34, v60, v66
	v_fmac_f32_e32 v35, v61, v66
	v_fmac_f32_e32 v36, v62, v66
	v_fmac_f32_e32 v37, v63, v66
	v_fmac_f32_e32 v38, v64, v66
	s_waitcnt vmcnt(1)
; __device__ __forceinline__ float bf2f(bfu h) { return __uint_as_float(((unsigned)h) << 16); }
; __device__ __forceinline__ float sigm(float x) { return 1.f / (1.f + __expf(-x)); }
;   __device__ __forceinline__ bfu* glu() const { return (bfu*)(b + L::o_glu); }
; template <int G>
; __device__ __forceinline__ void p2_conformer(const Params& P, const Ptrs<G>& w, int layer, int item, float* cv, int kslot) {
;     ...
;     for (int sr = 0; sr < 62; ++sr) {
;       const int s = t0 - 30 + sr;
;       float h0 = 0.f;
;       if (s >= 0) {
;         const bfu* gp = w.glu() + (seqbase + s) * 1024 + c;
;         h0 = bf2f(gp[0]) * sigm(bf2f(gp[512]));
;       }
; #pragma unroll
;       for (int tr = 0; tr < 32; ++tr) {
;         const int j = sr - tr;
;         if (j >= 0 && j <= 30) a[tr] += wj[j] * h0;
;       }
;     }
	v_lshlrev_b32_e32 v65, 16, v65
	v_mul_f32_e32 v65, 0xbfb8aa3b, v65
	v_exp_f32_e32 v65, v65
	s_nop 0
	v_add_f32_e32 v65, 1.0, v65
	v_div_scale_f32 v66, s[72:73], v65, v65, 1.0
	v_rcp_f32_e32 v67, v66
	s_nop 0
	v_fma_f32 v68, -v66, v67, 1.0
	v_fmac_f32_e32 v67, v68, v67
	v_div_scale_f32 v68, vcc, 1.0, v65, 1.0
	v_mul_f32_e32 v69, v68, v67
	v_fma_f32 v72, -v66, v69, v68
	v_fmac_f32_e32 v69, v72, v67
	v_fma_f32 v66, -v66, v69, v68
	v_div_fmas_f32 v66, v66, v67, v69
	v_div_fixup_f32 v65, v66, v65, 1.0
	v_lshl_add_u64 v[100:101], v[70:71], 0, s[100:101]
	global_load_ushort v66, v[70:71], off offset:2048
	global_load_ushort v102, v[100:101], off offset:2048
	s_waitcnt vmcnt(1)
	v_lshlrev_b32_e32 v66, 16, v66
	v_mul_f32_e32 v65, v65, v66
	v_fmac_f32_e32 v7, v64, v65
	v_add_co_u32_e32 v64, vcc, s17, v4
	v_fmac_f32_e32 v12, v6, v65
	v_fmac_f32_e32 v13, v39, v65
	v_fmac_f32_e32 v14, v40, v65
	v_fmac_f32_e32 v15, v41, v65
	v_fmac_f32_e32 v17, v42, v65
	v_fmac_f32_e32 v18, v43, v65
	v_fmac_f32_e32 v19, v44, v65
	v_fmac_f32_e32 v20, v45, v65
	v_fmac_f32_e32 v21, v47, v65
	v_fmac_f32_e32 v22, v46, v65
	v_fmac_f32_e32 v23, v48, v65
	v_fmac_f32_e32 v24, v49, v65
	v_fmac_f32_e32 v25, v50, v65
	v_fmac_f32_e32 v26, v51, v65
	v_fmac_f32_e32 v27, v52, v65
	v_fmac_f32_e32 v28, v53, v65
	v_fmac_f32_e32 v29, v54, v65
	v_fmac_f32_e32 v30, v55, v65
	v_fmac_f32_e32 v31, v56, v65
	v_fmac_f32_e32 v32, v57, v65
	v_fmac_f32_e32 v33, v58, v65
	v_fmac_f32_e32 v34, v59, v65
	v_fmac_f32_e32 v35, v60, v65
	v_fmac_f32_e32 v36, v61, v65
	v_fmac_f32_e32 v37, v62, v65
	v_fmac_f32_e32 v38, v63, v65
	v_addc_co_u32_e32 v65, vcc, 0, v5, vcc
	v_lshl_add_u64 v[100:101], v[64:65], 0, s[100:101]
	global_load_ushort v66, v[64:65], off offset:1024
	global_load_ushort v102, v[100:101], off offset:1024
	s_movk_i32 s17, 0x4000
	s_waitcnt vmcnt(1)
	v_lshlrev_b32_e32 v66, 16, v66
	v_mul_f32_e32 v66, 0xbfb8aa3b, v66
	v_exp_f32_e32 v66, v66
	s_nop 0
	v_add_f32_e32 v66, 1.0, v66
	v_div_scale_f32 v67, s[72:73], v66, v66, 1.0
	v_rcp_f32_e32 v68, v67
	s_nop 0
	v_fma_f32 v69, -v67, v68, 1.0
	v_fmac_f32_e32 v68, v69, v68
	v_div_scale_f32 v69, vcc, 1.0, v66, 1.0
	v_mul_f32_e32 v70, v69, v68
	v_fma_f32 v71, -v67, v70, v69
	v_fmac_f32_e32 v70, v71, v68
	v_fma_f32 v67, -v67, v70, v69
	v_div_fmas_f32 v67, v67, v68, v70
	v_div_fixup_f32 v68, v67, v66, 1.0
	v_add_co_u32_e32 v66, vcc, s17, v4
	s_nop 1
	v_addc_co_u32_e32 v67, vcc, 0, v5, vcc
	v_lshl_add_u64 v[100:101], v[66:67], 0, s[100:101]
	global_load_ushort v69, v[66:67], off offset:-4096
	global_load_ushort v102, v[100:101], off offset:-4096
	s_waitcnt vmcnt(1)
	v_lshlrev_b32_e32 v69, 16, v69
	v_mul_f32_e32 v68, v68, v69
	v_fmac_f32_e32 v7, v63, v68
	v_lshl_add_u64 v[100:101], v[64:65], 0, s[100:101]
	global_load_ushort v63, v[64:65], off offset:3072
	global_load_ushort v102, v[100:101], off offset:3072
	v_fmac_f32_e32 v13, v6, v68
	v_lshl_add_u64 v[100:101], v[64:65], 0, s[100:101]
	global_load_ushort v64, v[64:65], off offset:2048
	global_load_ushort v102, v[100:101], off offset:2048
	v_fmac_f32_e32 v14, v39, v68
	v_fmac_f32_e32 v15, v40, v68
	v_fmac_f32_e32 v17, v41, v68
	v_fmac_f32_e32 v18, v42, v68
	v_fmac_f32_e32 v19, v43, v68
	v_fmac_f32_e32 v20, v44, v68
	v_fmac_f32_e32 v21, v45, v68
	v_fmac_f32_e32 v22, v47, v68
	v_fmac_f32_e32 v23, v46, v68
	v_fmac_f32_e32 v24, v48, v68
	v_fmac_f32_e32 v25, v49, v68
	v_fmac_f32_e32 v26, v50, v68
	v_fmac_f32_e32 v27, v51, v68
	v_fmac_f32_e32 v28, v52, v68
	v_fmac_f32_e32 v29, v53, v68
	v_fmac_f32_e32 v30, v54, v68
	v_fmac_f32_e32 v31, v55, v68
	v_fmac_f32_e32 v32, v56, v68
	v_fmac_f32_e32 v33, v57, v68
	v_fmac_f32_e32 v34, v58, v68
	v_fmac_f32_e32 v35, v59, v68
	v_fmac_f32_e32 v36, v60, v68
	v_fmac_f32_e32 v37, v61, v68
	v_fmac_f32_e32 v38, v62, v68
	s_waitcnt vmcnt(3)
	v_lshlrev_b32_e32 v63, 16, v63
	v_mul_f32_e32 v63, 0xbfb8aa3b, v63
	v_exp_f32_e32 v63, v63
	s_waitcnt vmcnt(1)
	v_lshlrev_b32_e32 v64, 16, v64
	v_add_f32_e32 v63, 1.0, v63
	v_div_scale_f32 v68, s[72:73], v63, v63, 1.0
	v_rcp_f32_e32 v69, v68
	s_nop 0
	v_fma_f32 v70, -v68, v69, 1.0
	v_fmac_f32_e32 v69, v70, v69
	v_div_scale_f32 v70, vcc, 1.0, v63, 1.0
	v_mul_f32_e32 v71, v70, v69
	v_fma_f32 v72, -v68, v71, v70
	v_fmac_f32_e32 v71, v72, v69
	v_fma_f32 v68, -v68, v71, v70
	v_div_fmas_f32 v68, v68, v69, v71
	v_div_fixup_f32 v63, v68, v63, 1.0
	v_mul_f32_e32 v63, v63, v64
	v_fmac_f32_e32 v7, v62, v63
	v_lshl_add_u64 v[100:101], v[66:67], 0, s[100:101]
	global_load_ushort v62, v[66:67], off offset:1024
	global_load_ushort v102, v[100:101], off offset:1024
	v_fmac_f32_e32 v14, v6, v63
	v_fmac_f32_e32 v15, v39, v63
	v_fmac_f32_e32 v17, v40, v63
	v_fmac_f32_e32 v18, v41, v63
	v_fmac_f32_e32 v19, v42, v63
	v_fmac_f32_e32 v20, v43, v63
	v_fmac_f32_e32 v21, v44, v63
	v_fmac_f32_e32 v22, v45, v63
	v_fmac_f32_e32 v23, v47, v63
	v_fmac_f32_e32 v24, v46, v63
	v_fmac_f32_e32 v25, v48, v63
	v_fmac_f32_e32 v26, v49, v63
	v_fmac_f32_e32 v27, v50, v63
	v_fmac_f32_e32 v28, v51, v63
	v_fmac_f32_e32 v29, v52, v63
	v_fmac_f32_e32 v30, v53, v63
	v_fmac_f32_e32 v31, v54, v63
	v_fmac_f32_e32 v32, v55, v63
	v_fmac_f32_e32 v33, v56, v63
	v_fmac_f32_e32 v34, v57, v63
	v_fmac_f32_e32 v35, v58, v63
	v_fmac_f32_e32 v36, v59, v63
	v_fmac_f32_e32 v37, v60, v63
	v_fmac_f32_e32 v38, v61, v63
	s_waitcnt vmcnt(1)
	v_lshlrev_b32_e32 v62, 16, v62
	v_mul_f32_e32 v62, 0xbfb8aa3b, v62
	v_exp_f32_e32 v62, v62
	s_nop 0
	v_add_f32_e32 v62, 1.0, v62
	v_div_scale_f32 v63, s[72:73], v62, v62, 1.0
	v_rcp_f32_e32 v64, v63
	s_nop 0
	v_fma_f32 v65, -v63, v64, 1.0
	v_fmac_f32_e32 v64, v65, v64
	v_div_scale_f32 v65, vcc, 1.0, v62, 1.0
	v_mul_f32_e32 v68, v65, v64
	v_fma_f32 v69, -v63, v68, v65
	v_fmac_f32_e32 v68, v69, v64
	v_fma_f32 v63, -v63, v68, v65
	v_div_fmas_f32 v63, v63, v64, v68
	v_div_fixup_f32 v62, v63, v62, 1.0
	v_lshl_add_u64 v[100:101], v[66:67], 0, s[100:101]
	global_load_ushort v63, v[66:67], off
	global_load_ushort v102, v[100:101], off
	s_waitcnt vmcnt(1)
; __device__ __forceinline__ float bf2f(bfu h) { return __uint_as_float(((unsigned)h) << 16); }
; __device__ __forceinline__ float sigm(float x) { return 1.f / (1.f + __expf(-x)); }
;   __device__ __forceinline__ bfu* glu() const { return (bfu*)(b + L::o_glu); }
; template <int G>
; __device__ __forceinline__ void p2_conformer(const Params& P, const Ptrs<G>& w, int layer, int item, float* cv, int kslot) {
;     ...
;     for (int sr = 0; sr < 62; ++sr) {
;       const int s = t0 - 30 + sr;
;       float h0 = 0.f;
;       if (s >= 0) {
;         const bfu* gp = w.glu() + (seqbase + s) * 1024 + c;
;         h0 = bf2f(gp[0]) * sigm(bf2f(gp[512]));
;       }
; #pragma unroll
;       for (int tr = 0; tr < 32; ++tr) {
;         const int j = sr - tr;
;         if (j >= 0 && j <= 30) a[tr] += wj[j] * h0;
;       }
;     }
	v_lshlrev_b32_e32 v63, 16, v63
	v_mul_f32_e32 v62, v62, v63
	v_fmac_f32_e32 v7, v61, v62
	v_lshl_add_u64 v[100:101], v[66:67], 0, s[100:101]
	global_load_ushort v61, v[66:67], off offset:3072
	global_load_ushort v102, v[100:101], off offset:3072
	v_fmac_f32_e32 v15, v6, v62
	v_fmac_f32_e32 v17, v39, v62
	v_fmac_f32_e32 v18, v40, v62
	v_fmac_f32_e32 v19, v41, v62
	v_fmac_f32_e32 v20, v42, v62
	v_fmac_f32_e32 v21, v43, v62
	v_fmac_f32_e32 v22, v44, v62
	v_fmac_f32_e32 v23, v45, v62
	v_fmac_f32_e32 v24, v47, v62
	v_fmac_f32_e32 v25, v46, v62
	v_fmac_f32_e32 v26, v48, v62
	v_fmac_f32_e32 v27, v49, v62
	v_fmac_f32_e32 v28, v50, v62
	v_fmac_f32_e32 v29, v51, v62
	v_fmac_f32_e32 v30, v52, v62
	v_fmac_f32_e32 v31, v53, v62
	v_fmac_f32_e32 v32, v54, v62
	v_fmac_f32_e32 v33, v55, v62
	v_fmac_f32_e32 v34, v56, v62
	v_fmac_f32_e32 v35, v57, v62
	v_fmac_f32_e32 v36, v58, v62
	v_fmac_f32_e32 v37, v59, v62
	v_fmac_f32_e32 v38, v60, v62
	s_waitcnt vmcnt(1)
	v_lshlrev_b32_e32 v61, 16, v61
	v_mul_f32_e32 v61, 0xbfb8aa3b, v61
	v_exp_f32_e32 v61, v61
	s_nop 0
	v_add_f32_e32 v61, 1.0, v61
	v_div_scale_f32 v62, s[72:73], v61, v61, 1.0
	v_rcp_f32_e32 v63, v62
	s_movk_i32 s72, 0x5000
	v_fma_f32 v64, -v62, v63, 1.0
	v_fmac_f32_e32 v63, v64, v63
	v_div_scale_f32 v64, vcc, 1.0, v61, 1.0
	v_mul_f32_e32 v65, v64, v63
	v_fma_f32 v68, -v62, v65, v64
	v_fmac_f32_e32 v65, v68, v63
	v_fma_f32 v62, -v62, v65, v64
	v_div_fmas_f32 v62, v62, v63, v65
	v_div_fixup_f32 v61, v62, v61, 1.0
	v_lshl_add_u64 v[100:101], v[66:67], 0, s[100:101]
	global_load_ushort v62, v[66:67], off offset:2048
	global_load_ushort v102, v[100:101], off offset:2048
	s_waitcnt vmcnt(1)
	v_lshlrev_b32_e32 v62, 16, v62
	v_mul_f32_e32 v61, v61, v62
	v_fmac_f32_e32 v7, v60, v61
	v_add_co_u32_e32 v60, vcc, s72, v4
	v_fmac_f32_e32 v17, v6, v61
	v_fmac_f32_e32 v18, v39, v61
	v_fmac_f32_e32 v19, v40, v61
	v_fmac_f32_e32 v20, v41, v61
	v_fmac_f32_e32 v21, v42, v61
	v_fmac_f32_e32 v22, v43, v61
	v_fmac_f32_e32 v23, v44, v61
	v_fmac_f32_e32 v24, v45, v61
	v_fmac_f32_e32 v25, v47, v61
	v_fmac_f32_e32 v26, v46, v61
	v_fmac_f32_e32 v27, v48, v61
	v_fmac_f32_e32 v28, v49, v61
	v_fmac_f32_e32 v29, v50, v61
	v_fmac_f32_e32 v30, v51, v61
	v_fmac_f32_e32 v31, v52, v61
	v_fmac_f32_e32 v32, v53, v61
	v_fmac_f32_e32 v33, v54, v61
	v_fmac_f32_e32 v34, v55, v61
	v_fmac_f32_e32 v35, v56, v61
	v_fmac_f32_e32 v36, v57, v61
	v_fmac_f32_e32 v37, v58, v61
	v_fmac_f32_e32 v38, v59, v61
	v_addc_co_u32_e32 v61, vcc, 0, v5, vcc
	v_lshl_add_u64 v[100:101], v[60:61], 0, s[100:101]
	global_load_ushort v62, v[60:61], off offset:1024
	global_load_ushort v102, v[100:101], off offset:1024
	s_waitcnt vmcnt(1)
	v_lshlrev_b32_e32 v62, 16, v62
	v_mul_f32_e32 v62, 0xbfb8aa3b, v62
	v_exp_f32_e32 v62, v62
	s_nop 0
	v_add_f32_e32 v62, 1.0, v62
	v_div_scale_f32 v63, s[72:73], v62, v62, 1.0
	v_rcp_f32_e32 v64, v63
	s_nop 0
	v_fma_f32 v65, -v63, v64, 1.0
	v_fmac_f32_e32 v64, v65, v64
	v_div_scale_f32 v65, vcc, 1.0, v62, 1.0
	v_mul_f32_e32 v66, v65, v64
	v_fma_f32 v67, -v63, v66, v65
	v_fmac_f32_e32 v66, v67, v64
	v_fma_f32 v63, -v63, v66, v65
	v_div_fmas_f32 v63, v63, v64, v66
	v_div_fixup_f32 v64, v63, v62, 1.0
	v_add_co_u32_e32 v62, vcc, s16, v4
	s_nop 1
	v_addc_co_u32_e32 v63, vcc, 0, v5, vcc
	v_lshl_add_u64 v[100:101], v[62:63], 0, s[100:101]
	global_load_ushort v65, v[62:63], off offset:-4096
	global_load_ushort v102, v[100:101], off offset:-4096
	s_waitcnt vmcnt(1)
	v_lshlrev_b32_e32 v65, 16, v65
	v_mul_f32_e32 v64, v64, v65
	v_fmac_f32_e32 v7, v59, v64
	v_lshl_add_u64 v[100:101], v[60:61], 0, s[100:101]
	global_load_ushort v59, v[60:61], off offset:3072
	global_load_ushort v102, v[100:101], off offset:3072
	v_fmac_f32_e32 v18, v6, v64
	v_lshl_add_u64 v[100:101], v[60:61], 0, s[100:101]
	global_load_ushort v60, v[60:61], off offset:2048
	global_load_ushort v102, v[100:101], off offset:2048
	v_fmac_f32_e32 v19, v39, v64
	v_fmac_f32_e32 v20, v40, v64
	v_fmac_f32_e32 v21, v41, v64
	v_fmac_f32_e32 v22, v42, v64
	v_fmac_f32_e32 v23, v43, v64
	v_fmac_f32_e32 v24, v44, v64
	v_fmac_f32_e32 v25, v45, v64
	v_fmac_f32_e32 v26, v47, v64
	v_fmac_f32_e32 v27, v46, v64
	v_fmac_f32_e32 v28, v48, v64
	v_fmac_f32_e32 v29, v49, v64
	v_fmac_f32_e32 v30, v50, v64
	v_fmac_f32_e32 v31, v51, v64
	v_fmac_f32_e32 v32, v52, v64
	v_fmac_f32_e32 v33, v53, v64
	v_fmac_f32_e32 v34, v54, v64
	v_fmac_f32_e32 v35, v55, v64
	v_fmac_f32_e32 v36, v56, v64
	v_fmac_f32_e32 v37, v57, v64
	v_fmac_f32_e32 v38, v58, v64
	s_waitcnt vmcnt(3)
	v_lshlrev_b32_e32 v59, 16, v59
	v_mul_f32_e32 v59, 0xbfb8aa3b, v59
	v_exp_f32_e32 v59, v59
	s_waitcnt vmcnt(1)
	v_lshlrev_b32_e32 v60, 16, v60
	v_add_f32_e32 v59, 1.0, v59
	v_div_scale_f32 v64, s[72:73], v59, v59, 1.0
	v_rcp_f32_e32 v65, v64
	s_nop 0
	v_fma_f32 v66, -v64, v65, 1.0
	v_fmac_f32_e32 v65, v66, v65
	v_div_scale_f32 v66, vcc, 1.0, v59, 1.0
	v_mul_f32_e32 v67, v66, v65
	v_fma_f32 v68, -v64, v67, v66
	v_fmac_f32_e32 v67, v68, v65
	v_fma_f32 v64, -v64, v67, v66
	v_div_fmas_f32 v64, v64, v65, v67
	v_div_fixup_f32 v59, v64, v59, 1.0
	v_mul_f32_e32 v59, v59, v60
	v_fmac_f32_e32 v7, v58, v59
	v_lshl_add_u64 v[100:101], v[62:63], 0, s[100:101]
	global_load_ushort v58, v[62:63], off offset:1024
	global_load_ushort v102, v[100:101], off offset:1024
	v_fmac_f32_e32 v19, v6, v59
	v_fmac_f32_e32 v20, v39, v59
	v_fmac_f32_e32 v21, v40, v59
	v_fmac_f32_e32 v22, v41, v59
	v_fmac_f32_e32 v23, v42, v59
	v_fmac_f32_e32 v24, v43, v59
	v_fmac_f32_e32 v25, v44, v59
	v_fmac_f32_e32 v26, v45, v59
	v_fmac_f32_e32 v27, v47, v59
	v_fmac_f32_e32 v28, v46, v59
	v_fmac_f32_e32 v29, v48, v59
	v_fmac_f32_e32 v30, v49, v59
	v_fmac_f32_e32 v31, v50, v59
	v_fmac_f32_e32 v32, v51, v59
	v_fmac_f32_e32 v33, v52, v59
	v_fmac_f32_e32 v34, v53, v59
	v_fmac_f32_e32 v35, v54, v59
	v_fmac_f32_e32 v36, v55, v59
	v_fmac_f32_e32 v37, v56, v59
	v_fmac_f32_e32 v38, v57, v59
	s_waitcnt vmcnt(1)
; __device__ __forceinline__ float bf2f(bfu h) { return __uint_as_float(((unsigned)h) << 16); }
; __device__ __forceinline__ float sigm(float x) { return 1.f / (1.f + __expf(-x)); }
;   __device__ __forceinline__ bfu* glu() const { return (bfu*)(b + L::o_glu); }
; template <int G>
; __device__ __forceinline__ void p2_conformer(const Params& P, const Ptrs<G>& w, int layer, int item, float* cv, int kslot) {
;     ...
;     for (int sr = 0; sr < 62; ++sr) {
;       const int s = t0 - 30 + sr;
;       float h0 = 0.f;
;       if (s >= 0) {
;         const bfu* gp = w.glu() + (seqbase + s) * 1024 + c;
;         h0 = bf2f(gp[0]) * sigm(bf2f(gp[512]));
;       }
; #pragma unroll
;       for (int tr = 0; tr < 32; ++tr) {
;         const int j = sr - tr;
;         if (j >= 0 && j <= 30) a[tr] += wj[j] * h0;
;       }
;     }
	v_lshlrev_b32_e32 v58, 16, v58
	v_mul_f32_e32 v58, 0xbfb8aa3b, v58
	v_exp_f32_e32 v58, v58
	s_nop 0
	v_add_f32_e32 v58, 1.0, v58
	v_div_scale_f32 v59, s[72:73], v58, v58, 1.0
	v_rcp_f32_e32 v60, v59
	s_nop 0
	v_fma_f32 v61, -v59, v60, 1.0
	v_fmac_f32_e32 v60, v61, v60
	v_div_scale_f32 v61, vcc, 1.0, v58, 1.0
	v_mul_f32_e32 v64, v61, v60
	v_fma_f32 v65, -v59, v64, v61
	v_fmac_f32_e32 v64, v65, v60
	v_fma_f32 v59, -v59, v64, v61
	v_div_fmas_f32 v59, v59, v60, v64
	v_div_fixup_f32 v58, v59, v58, 1.0
	v_lshl_add_u64 v[100:101], v[62:63], 0, s[100:101]
	global_load_ushort v59, v[62:63], off
	global_load_ushort v102, v[100:101], off
	s_waitcnt vmcnt(1)
	v_lshlrev_b32_e32 v59, 16, v59
	v_mul_f32_e32 v58, v58, v59
	v_fmac_f32_e32 v7, v57, v58
	v_lshl_add_u64 v[100:101], v[62:63], 0, s[100:101]
	global_load_ushort v57, v[62:63], off offset:3072
	global_load_ushort v102, v[100:101], off offset:3072
	v_fmac_f32_e32 v20, v6, v58
	v_fmac_f32_e32 v21, v39, v58
	v_fmac_f32_e32 v22, v40, v58
	v_fmac_f32_e32 v23, v41, v58
	v_fmac_f32_e32 v24, v42, v58
	v_fmac_f32_e32 v25, v43, v58
	v_fmac_f32_e32 v26, v44, v58
	v_fmac_f32_e32 v27, v45, v58
	v_fmac_f32_e32 v28, v47, v58
	v_fmac_f32_e32 v29, v46, v58
	v_fmac_f32_e32 v30, v48, v58
	v_fmac_f32_e32 v31, v49, v58
	v_fmac_f32_e32 v32, v50, v58
	v_fmac_f32_e32 v33, v51, v58
	v_fmac_f32_e32 v34, v52, v58
	v_fmac_f32_e32 v35, v53, v58
	v_fmac_f32_e32 v36, v54, v58
	v_fmac_f32_e32 v37, v55, v58
	v_fmac_f32_e32 v38, v56, v58
	s_waitcnt vmcnt(1)
	v_lshlrev_b32_e32 v57, 16, v57
	v_mul_f32_e32 v57, 0xbfb8aa3b, v57
	v_exp_f32_e32 v57, v57
	s_nop 0
	v_add_f32_e32 v57, 1.0, v57
	v_div_scale_f32 v58, s[72:73], v57, v57, 1.0
	v_rcp_f32_e32 v59, v58
	s_movk_i32 s72, 0x7000
	v_fma_f32 v60, -v58, v59, 1.0
	v_fmac_f32_e32 v59, v60, v59
	v_div_scale_f32 v60, vcc, 1.0, v57, 1.0
	v_mul_f32_e32 v61, v60, v59
	v_fma_f32 v64, -v58, v61, v60
	v_fmac_f32_e32 v61, v64, v59
	v_fma_f32 v58, -v58, v61, v60
	v_div_fmas_f32 v58, v58, v59, v61
	v_div_fixup_f32 v57, v58, v57, 1.0
	v_lshl_add_u64 v[100:101], v[62:63], 0, s[100:101]
	global_load_ushort v58, v[62:63], off offset:2048
	global_load_ushort v102, v[100:101], off offset:2048
	s_waitcnt vmcnt(1)
	v_lshlrev_b32_e32 v58, 16, v58
	v_mul_f32_e32 v57, v57, v58
	v_fmac_f32_e32 v7, v56, v57
	v_add_co_u32_e32 v56, vcc, s72, v4
	v_fmac_f32_e32 v21, v6, v57
	v_fmac_f32_e32 v22, v39, v57
	v_fmac_f32_e32 v23, v40, v57
	v_fmac_f32_e32 v24, v41, v57
	v_fmac_f32_e32 v25, v42, v57
	v_fmac_f32_e32 v26, v43, v57
	v_fmac_f32_e32 v27, v44, v57
	v_fmac_f32_e32 v28, v45, v57
	v_fmac_f32_e32 v29, v47, v57
	v_fmac_f32_e32 v30, v46, v57
	v_fmac_f32_e32 v31, v48, v57
	v_fmac_f32_e32 v32, v49, v57
	v_fmac_f32_e32 v33, v50, v57
	v_fmac_f32_e32 v34, v51, v57
	v_fmac_f32_e32 v35, v52, v57
	v_fmac_f32_e32 v36, v53, v57
	v_fmac_f32_e32 v37, v54, v57
	v_fmac_f32_e32 v38, v55, v57
	v_addc_co_u32_e32 v57, vcc, 0, v5, vcc
	v_lshl_add_u64 v[100:101], v[56:57], 0, s[100:101]
	global_load_ushort v58, v[56:57], off offset:1024
	global_load_ushort v102, v[100:101], off offset:1024
	s_waitcnt vmcnt(1)
	v_lshlrev_b32_e32 v58, 16, v58
	v_mul_f32_e32 v58, 0xbfb8aa3b, v58
	v_exp_f32_e32 v58, v58
	s_nop 0
	v_add_f32_e32 v58, 1.0, v58
	v_div_scale_f32 v59, s[72:73], v58, v58, 1.0
	v_rcp_f32_e32 v60, v59
	s_nop 0
	v_fma_f32 v61, -v59, v60, 1.0
	v_fmac_f32_e32 v60, v61, v60
	v_div_scale_f32 v61, vcc, 1.0, v58, 1.0
	v_mul_f32_e32 v62, v61, v60
	v_fma_f32 v63, -v59, v62, v61
	v_fmac_f32_e32 v62, v63, v60
	v_fma_f32 v59, -v59, v62, v61
	v_div_fmas_f32 v59, v59, v60, v62
	v_div_fixup_f32 v60, v59, v58, 1.0
	v_add_co_u32_e32 v58, vcc, s88, v4
	s_nop 1
	v_addc_co_u32_e32 v59, vcc, 0, v5, vcc
	v_lshl_add_u64 v[100:101], v[58:59], 0, s[100:101]
	global_load_ushort v61, v[58:59], off offset:-4096
	global_load_ushort v102, v[100:101], off offset:-4096
	s_waitcnt vmcnt(1)
	v_lshlrev_b32_e32 v61, 16, v61
	v_mul_f32_e32 v60, v60, v61
	v_fmac_f32_e32 v7, v55, v60
	v_lshl_add_u64 v[100:101], v[56:57], 0, s[100:101]
	global_load_ushort v55, v[56:57], off offset:3072
	global_load_ushort v102, v[100:101], off offset:3072
	v_fmac_f32_e32 v22, v6, v60
	v_lshl_add_u64 v[100:101], v[56:57], 0, s[100:101]
	global_load_ushort v56, v[56:57], off offset:2048
	global_load_ushort v102, v[100:101], off offset:2048
	v_fmac_f32_e32 v23, v39, v60
	v_fmac_f32_e32 v24, v40, v60
	v_fmac_f32_e32 v25, v41, v60
	v_fmac_f32_e32 v26, v42, v60
	v_fmac_f32_e32 v27, v43, v60
	v_fmac_f32_e32 v28, v44, v60
	v_fmac_f32_e32 v29, v45, v60
	v_fmac_f32_e32 v30, v47, v60
	v_fmac_f32_e32 v31, v46, v60
	v_fmac_f32_e32 v32, v48, v60
	v_fmac_f32_e32 v33, v49, v60
	v_fmac_f32_e32 v34, v50, v60
	v_fmac_f32_e32 v35, v51, v60
	v_fmac_f32_e32 v36, v52, v60
	v_fmac_f32_e32 v37, v53, v60
	v_fmac_f32_e32 v38, v54, v60
	s_waitcnt vmcnt(3)
	v_lshlrev_b32_e32 v55, 16, v55
	v_mul_f32_e32 v55, 0xbfb8aa3b, v55
	v_exp_f32_e32 v55, v55
	s_waitcnt vmcnt(1)
	v_lshlrev_b32_e32 v56, 16, v56
	v_add_f32_e32 v55, 1.0, v55
	v_div_scale_f32 v60, s[72:73], v55, v55, 1.0
	v_rcp_f32_e32 v61, v60
	s_nop 0
	v_fma_f32 v62, -v60, v61, 1.0
	v_fmac_f32_e32 v61, v62, v61
	v_div_scale_f32 v62, vcc, 1.0, v55, 1.0
	v_mul_f32_e32 v63, v62, v61
	v_fma_f32 v64, -v60, v63, v62
	v_fmac_f32_e32 v63, v64, v61
	v_fma_f32 v60, -v60, v63, v62
	v_div_fmas_f32 v60, v60, v61, v63
	v_div_fixup_f32 v55, v60, v55, 1.0
	v_mul_f32_e32 v55, v55, v56
	v_fmac_f32_e32 v7, v54, v55
	v_lshl_add_u64 v[100:101], v[58:59], 0, s[100:101]
	global_load_ushort v54, v[58:59], off offset:1024
	global_load_ushort v102, v[100:101], off offset:1024
	v_fmac_f32_e32 v23, v6, v55
	v_fmac_f32_e32 v24, v39, v55
	v_fmac_f32_e32 v25, v40, v55
	v_fmac_f32_e32 v26, v41, v55
	v_fmac_f32_e32 v27, v42, v55
	v_fmac_f32_e32 v28, v43, v55
	v_fmac_f32_e32 v29, v44, v55
	v_fmac_f32_e32 v30, v45, v55
	v_fmac_f32_e32 v31, v47, v55
	v_fmac_f32_e32 v32, v46, v55
	v_fmac_f32_e32 v33, v48, v55
	v_fmac_f32_e32 v34, v49, v55
	v_fmac_f32_e32 v35, v50, v55
	v_fmac_f32_e32 v36, v51, v55
	v_fmac_f32_e32 v37, v52, v55
	v_fmac_f32_e32 v38, v53, v55
	s_waitcnt vmcnt(1)
; __device__ __forceinline__ float bf2f(bfu h) { return __uint_as_float(((unsigned)h) << 16); }
; __device__ __forceinline__ float sigm(float x) { return 1.f / (1.f + __expf(-x)); }
;   __device__ __forceinline__ bfu* glu() const { return (bfu*)(b + L::o_glu); }
; template <int G>
; __device__ __forceinline__ void p2_conformer(const Params& P, const Ptrs<G>& w, int layer, int item, float* cv, int kslot) {
;     ...
;     for (int sr = 0; sr < 62; ++sr) {
;       const int s = t0 - 30 + sr;
;       float h0 = 0.f;
;       if (s >= 0) {
;         const bfu* gp = w.glu() + (seqbase + s) * 1024 + c;
;         h0 = bf2f(gp[0]) * sigm(bf2f(gp[512]));
;       }
; #pragma unroll
;       for (int tr = 0; tr < 32; ++tr) {
;         const int j = sr - tr;
;         if (j >= 0 && j <= 30) a[tr] += wj[j] * h0;
;       }
;     }
	v_lshlrev_b32_e32 v54, 16, v54
	v_mul_f32_e32 v54, 0xbfb8aa3b, v54
	v_exp_f32_e32 v54, v54
	s_nop 0
	v_add_f32_e32 v54, 1.0, v54
	v_div_scale_f32 v55, s[72:73], v54, v54, 1.0
	v_rcp_f32_e32 v56, v55
	s_nop 0
	v_fma_f32 v57, -v55, v56, 1.0
	v_fmac_f32_e32 v56, v57, v56
	v_div_scale_f32 v57, vcc, 1.0, v54, 1.0
	v_mul_f32_e32 v60, v57, v56
	v_fma_f32 v61, -v55, v60, v57
	v_fmac_f32_e32 v60, v61, v56
	v_fma_f32 v55, -v55, v60, v57
	v_div_fmas_f32 v55, v55, v56, v60
	v_div_fixup_f32 v54, v55, v54, 1.0
	v_lshl_add_u64 v[100:101], v[58:59], 0, s[100:101]
	global_load_ushort v55, v[58:59], off
	global_load_ushort v102, v[100:101], off
	s_waitcnt vmcnt(1)
	v_lshlrev_b32_e32 v55, 16, v55
	v_mul_f32_e32 v54, v54, v55
	v_fmac_f32_e32 v7, v53, v54
	v_lshl_add_u64 v[100:101], v[58:59], 0, s[100:101]
	global_load_ushort v53, v[58:59], off offset:3072
	global_load_ushort v102, v[100:101], off offset:3072
	v_fmac_f32_e32 v24, v6, v54
	v_fmac_f32_e32 v25, v39, v54
	v_fmac_f32_e32 v26, v40, v54
	v_fmac_f32_e32 v27, v41, v54
	v_fmac_f32_e32 v28, v42, v54
	v_fmac_f32_e32 v29, v43, v54
	v_fmac_f32_e32 v30, v44, v54
	v_fmac_f32_e32 v31, v45, v54
	v_fmac_f32_e32 v32, v47, v54
	v_fmac_f32_e32 v33, v46, v54
	v_fmac_f32_e32 v34, v48, v54
	v_fmac_f32_e32 v35, v49, v54
	v_fmac_f32_e32 v36, v50, v54
	v_fmac_f32_e32 v37, v51, v54
	v_fmac_f32_e32 v38, v52, v54
	s_waitcnt vmcnt(1)
	v_lshlrev_b32_e32 v53, 16, v53
	v_mul_f32_e32 v53, 0xbfb8aa3b, v53
	v_exp_f32_e32 v53, v53
	s_nop 0
	v_add_f32_e32 v53, 1.0, v53
	v_div_scale_f32 v54, s[72:73], v53, v53, 1.0
	v_rcp_f32_e32 v55, v54
	s_mov_b32 s72, 0x9000
	v_fma_f32 v56, -v54, v55, 1.0
	v_fmac_f32_e32 v55, v56, v55
	v_div_scale_f32 v56, vcc, 1.0, v53, 1.0
	v_mul_f32_e32 v57, v56, v55
	v_fma_f32 v60, -v54, v57, v56
	v_fmac_f32_e32 v57, v60, v55
	v_fma_f32 v54, -v54, v57, v56
	v_div_fmas_f32 v54, v54, v55, v57
	v_div_fixup_f32 v53, v54, v53, 1.0
	v_lshl_add_u64 v[100:101], v[58:59], 0, s[100:101]
	global_load_ushort v54, v[58:59], off offset:2048
	global_load_ushort v102, v[100:101], off offset:2048
	s_waitcnt vmcnt(1)
	v_lshlrev_b32_e32 v54, 16, v54
	v_mul_f32_e32 v53, v53, v54
	v_fmac_f32_e32 v7, v52, v53
	v_add_co_u32_e32 v52, vcc, s72, v4
	v_fmac_f32_e32 v25, v6, v53
	v_fmac_f32_e32 v26, v39, v53
	v_fmac_f32_e32 v27, v40, v53
	v_fmac_f32_e32 v28, v41, v53
	v_fmac_f32_e32 v29, v42, v53
	v_fmac_f32_e32 v30, v43, v53
	v_fmac_f32_e32 v31, v44, v53
	v_fmac_f32_e32 v32, v45, v53
	v_fmac_f32_e32 v33, v47, v53
	v_fmac_f32_e32 v34, v46, v53
	v_fmac_f32_e32 v35, v48, v53
	v_fmac_f32_e32 v36, v49, v53
	v_fmac_f32_e32 v37, v50, v53
	v_fmac_f32_e32 v38, v51, v53
	v_addc_co_u32_e32 v53, vcc, 0, v5, vcc
	v_lshl_add_u64 v[100:101], v[52:53], 0, s[100:101]
	global_load_ushort v54, v[52:53], off offset:1024
	global_load_ushort v102, v[100:101], off offset:1024
	s_waitcnt vmcnt(1)
	v_lshlrev_b32_e32 v54, 16, v54
	v_mul_f32_e32 v54, 0xbfb8aa3b, v54
	v_exp_f32_e32 v54, v54
	s_nop 0
	v_add_f32_e32 v54, 1.0, v54
	v_div_scale_f32 v55, s[72:73], v54, v54, 1.0
	v_rcp_f32_e32 v56, v55
	s_mov_b32 s72, 0xa000
	v_fma_f32 v57, -v55, v56, 1.0
	v_fmac_f32_e32 v56, v57, v56
	v_div_scale_f32 v57, vcc, 1.0, v54, 1.0
	v_mul_f32_e32 v58, v57, v56
	v_fma_f32 v59, -v55, v58, v57
	v_fmac_f32_e32 v58, v59, v56
	v_fma_f32 v55, -v55, v58, v57
	v_div_fmas_f32 v55, v55, v56, v58
	v_div_fixup_f32 v56, v55, v54, 1.0
	v_add_co_u32_e32 v54, vcc, s72, v4
	s_nop 1
	v_addc_co_u32_e32 v55, vcc, 0, v5, vcc
	v_lshl_add_u64 v[100:101], v[54:55], 0, s[100:101]
	global_load_ushort v57, v[54:55], off offset:-4096
	global_load_ushort v102, v[100:101], off offset:-4096
	s_waitcnt vmcnt(1)
	v_lshlrev_b32_e32 v57, 16, v57
	v_mul_f32_e32 v56, v56, v57
	v_fmac_f32_e32 v7, v51, v56
	v_lshl_add_u64 v[100:101], v[52:53], 0, s[100:101]
	global_load_ushort v51, v[52:53], off offset:3072
	global_load_ushort v102, v[100:101], off offset:3072
	v_fmac_f32_e32 v26, v6, v56
	v_lshl_add_u64 v[100:101], v[52:53], 0, s[100:101]
	global_load_ushort v52, v[52:53], off offset:2048
	global_load_ushort v102, v[100:101], off offset:2048
	v_fmac_f32_e32 v27, v39, v56
	v_fmac_f32_e32 v28, v40, v56
	v_fmac_f32_e32 v29, v41, v56
	v_fmac_f32_e32 v30, v42, v56
	v_fmac_f32_e32 v31, v43, v56
	v_fmac_f32_e32 v32, v44, v56
	v_fmac_f32_e32 v33, v45, v56
	v_fmac_f32_e32 v34, v47, v56
	v_fmac_f32_e32 v35, v46, v56
	v_fmac_f32_e32 v36, v48, v56
	v_fmac_f32_e32 v37, v49, v56
	v_fmac_f32_e32 v38, v50, v56
	s_waitcnt vmcnt(3)
	v_lshlrev_b32_e32 v51, 16, v51
	v_mul_f32_e32 v51, 0xbfb8aa3b, v51
	v_exp_f32_e32 v51, v51
	s_waitcnt vmcnt(1)
	v_lshlrev_b32_e32 v52, 16, v52
	v_add_f32_e32 v51, 1.0, v51
	v_div_scale_f32 v56, s[72:73], v51, v51, 1.0
	v_rcp_f32_e32 v57, v56
	s_nop 0
	v_fma_f32 v58, -v56, v57, 1.0
	v_fmac_f32_e32 v57, v58, v57
	v_div_scale_f32 v58, vcc, 1.0, v51, 1.0
	v_mul_f32_e32 v59, v58, v57
	v_fma_f32 v60, -v56, v59, v58
	v_fmac_f32_e32 v59, v60, v57
	v_fma_f32 v56, -v56, v59, v58
	v_div_fmas_f32 v56, v56, v57, v59
	v_div_fixup_f32 v51, v56, v51, 1.0
	v_mul_f32_e32 v51, v51, v52
	v_fmac_f32_e32 v7, v50, v51
	v_lshl_add_u64 v[100:101], v[54:55], 0, s[100:101]
	global_load_ushort v50, v[54:55], off offset:1024
	global_load_ushort v102, v[100:101], off offset:1024
	v_fmac_f32_e32 v27, v6, v51
	v_fmac_f32_e32 v28, v39, v51
	v_fmac_f32_e32 v29, v40, v51
	v_fmac_f32_e32 v30, v41, v51
	v_fmac_f32_e32 v31, v42, v51
	v_fmac_f32_e32 v32, v43, v51
	v_fmac_f32_e32 v33, v44, v51
	v_fmac_f32_e32 v34, v45, v51
	v_fmac_f32_e32 v35, v47, v51
	v_fmac_f32_e32 v36, v46, v51
	v_fmac_f32_e32 v37, v48, v51
	v_fmac_f32_e32 v38, v49, v51
	s_waitcnt vmcnt(1)
; __device__ __forceinline__ float bf2f(bfu h) { return __uint_as_float(((unsigned)h) << 16); }
; __device__ __forceinline__ float sigm(float x) { return 1.f / (1.f + __expf(-x)); }
;   __device__ __forceinline__ bfu* glu() const { return (bfu*)(b + L::o_glu); }
; template <int G>
; __device__ __forceinline__ void p2_conformer(const Params& P, const Ptrs<G>& w, int layer, int item, float* cv, int kslot) {
;     ...
;     for (int sr = 0; sr < 62; ++sr) {
;       const int s = t0 - 30 + sr;
;       float h0 = 0.f;
;       if (s >= 0) {
;         const bfu* gp = w.glu() + (seqbase + s) * 1024 + c;
;         h0 = bf2f(gp[0]) * sigm(bf2f(gp[512]));
;       }
; #pragma unroll
;       for (int tr = 0; tr < 32; ++tr) {
;         const int j = sr - tr;
;         if (j >= 0 && j <= 30) a[tr] += wj[j] * h0;
;       }
;     }
	v_lshlrev_b32_e32 v50, 16, v50
	v_mul_f32_e32 v50, 0xbfb8aa3b, v50
	v_exp_f32_e32 v50, v50
	s_nop 0
	v_add_f32_e32 v50, 1.0, v50
	v_div_scale_f32 v51, s[72:73], v50, v50, 1.0
	v_rcp_f32_e32 v52, v51
	s_nop 0
	v_fma_f32 v53, -v51, v52, 1.0
	v_fmac_f32_e32 v52, v53, v52
	v_div_scale_f32 v53, vcc, 1.0, v50, 1.0
	v_mul_f32_e32 v56, v53, v52
	v_fma_f32 v57, -v51, v56, v53
	v_fmac_f32_e32 v56, v57, v52
	v_fma_f32 v51, -v51, v56, v53
	v_div_fmas_f32 v51, v51, v52, v56
	v_div_fixup_f32 v50, v51, v50, 1.0
	v_lshl_add_u64 v[100:101], v[54:55], 0, s[100:101]
	global_load_ushort v51, v[54:55], off
	global_load_ushort v102, v[100:101], off
	s_waitcnt vmcnt(1)
	v_lshlrev_b32_e32 v51, 16, v51
	v_mul_f32_e32 v50, v50, v51
	v_fmac_f32_e32 v7, v49, v50
	v_lshl_add_u64 v[100:101], v[54:55], 0, s[100:101]
	global_load_ushort v49, v[54:55], off offset:3072
	global_load_ushort v102, v[100:101], off offset:3072
	v_fmac_f32_e32 v28, v6, v50
	v_fmac_f32_e32 v29, v39, v50
	v_fmac_f32_e32 v30, v40, v50
	v_fmac_f32_e32 v31, v41, v50
	v_fmac_f32_e32 v32, v42, v50
	v_fmac_f32_e32 v33, v43, v50
	v_fmac_f32_e32 v34, v44, v50
	v_fmac_f32_e32 v35, v45, v50
	v_fmac_f32_e32 v36, v47, v50
	v_fmac_f32_e32 v37, v46, v50
	v_fmac_f32_e32 v38, v48, v50
	s_waitcnt vmcnt(1)
	v_lshlrev_b32_e32 v49, 16, v49
	v_mul_f32_e32 v49, 0xbfb8aa3b, v49
	v_exp_f32_e32 v49, v49
	s_nop 0
	v_add_f32_e32 v49, 1.0, v49
	v_div_scale_f32 v50, s[72:73], v49, v49, 1.0
	v_rcp_f32_e32 v51, v50
	s_mov_b32 s72, 0xb000
	v_fma_f32 v52, -v50, v51, 1.0
	v_fmac_f32_e32 v51, v52, v51
	v_div_scale_f32 v52, vcc, 1.0, v49, 1.0
	v_mul_f32_e32 v53, v52, v51
	v_fma_f32 v56, -v50, v53, v52
	v_fmac_f32_e32 v53, v56, v51
	v_fma_f32 v50, -v50, v53, v52
	v_div_fmas_f32 v50, v50, v51, v53
	v_div_fixup_f32 v49, v50, v49, 1.0
	v_lshl_add_u64 v[100:101], v[54:55], 0, s[100:101]
	global_load_ushort v50, v[54:55], off offset:2048
	global_load_ushort v102, v[100:101], off offset:2048
	s_waitcnt vmcnt(1)
	v_lshlrev_b32_e32 v50, 16, v50
	v_mul_f32_e32 v49, v49, v50
	v_fmac_f32_e32 v7, v48, v49
	v_add_co_u32_e32 v48, vcc, s72, v4
	v_fmac_f32_e32 v29, v6, v49
	v_fmac_f32_e32 v30, v39, v49
	v_fmac_f32_e32 v31, v40, v49
	v_fmac_f32_e32 v32, v41, v49
	v_fmac_f32_e32 v33, v42, v49
	v_fmac_f32_e32 v34, v43, v49
	v_fmac_f32_e32 v35, v44, v49
	v_fmac_f32_e32 v36, v45, v49
	v_fmac_f32_e32 v37, v47, v49
	v_fmac_f32_e32 v38, v46, v49
	v_addc_co_u32_e32 v49, vcc, 0, v5, vcc
	v_lshl_add_u64 v[100:101], v[48:49], 0, s[100:101]
	global_load_ushort v50, v[48:49], off offset:1024
	global_load_ushort v102, v[100:101], off offset:1024
	s_waitcnt vmcnt(1)
	v_lshlrev_b32_e32 v50, 16, v50
	v_mul_f32_e32 v50, 0xbfb8aa3b, v50
	v_exp_f32_e32 v50, v50
	s_nop 0
	v_add_f32_e32 v50, 1.0, v50
	v_div_scale_f32 v51, s[72:73], v50, v50, 1.0
	v_rcp_f32_e32 v52, v51
	s_mov_b32 s72, 0xc000
	v_fma_f32 v53, -v51, v52, 1.0
	v_fmac_f32_e32 v52, v53, v52
	v_div_scale_f32 v53, vcc, 1.0, v50, 1.0
	v_mul_f32_e32 v54, v53, v52
	v_fma_f32 v55, -v51, v54, v53
	v_fmac_f32_e32 v54, v55, v52
	v_fma_f32 v51, -v51, v54, v53
	v_div_fmas_f32 v51, v51, v52, v54
	v_div_fixup_f32 v52, v51, v50, 1.0
	v_add_co_u32_e32 v50, vcc, s72, v4
	s_nop 1
	v_addc_co_u32_e32 v51, vcc, 0, v5, vcc
	v_lshl_add_u64 v[100:101], v[50:51], 0, s[100:101]
	global_load_ushort v53, v[50:51], off offset:-4096
	global_load_ushort v102, v[100:101], off offset:-4096
	s_waitcnt vmcnt(1)
	v_lshlrev_b32_e32 v53, 16, v53
	v_mul_f32_e32 v52, v52, v53
	v_fmac_f32_e32 v7, v46, v52
	v_lshl_add_u64 v[100:101], v[48:49], 0, s[100:101]
	global_load_ushort v46, v[48:49], off offset:3072
	global_load_ushort v102, v[100:101], off offset:3072
	v_fmac_f32_e32 v30, v6, v52
	v_lshl_add_u64 v[100:101], v[48:49], 0, s[100:101]
	global_load_ushort v48, v[48:49], off offset:2048
	global_load_ushort v102, v[100:101], off offset:2048
	v_fmac_f32_e32 v31, v39, v52
	v_fmac_f32_e32 v32, v40, v52
	v_fmac_f32_e32 v33, v41, v52
	v_fmac_f32_e32 v34, v42, v52
	v_fmac_f32_e32 v35, v43, v52
	v_fmac_f32_e32 v36, v44, v52
	v_fmac_f32_e32 v37, v45, v52
	v_fmac_f32_e32 v38, v47, v52
	s_waitcnt vmcnt(3)
	v_lshlrev_b32_e32 v46, 16, v46
	v_mul_f32_e32 v46, 0xbfb8aa3b, v46
	v_exp_f32_e32 v46, v46
	s_waitcnt vmcnt(1)
	v_lshlrev_b32_e32 v48, 16, v48
	v_add_f32_e32 v46, 1.0, v46
	v_div_scale_f32 v52, s[72:73], v46, v46, 1.0
	v_rcp_f32_e32 v53, v52
	s_nop 0
	v_fma_f32 v54, -v52, v53, 1.0
	v_fmac_f32_e32 v53, v54, v53
	v_div_scale_f32 v54, vcc, 1.0, v46, 1.0
	v_mul_f32_e32 v55, v54, v53
	v_fma_f32 v56, -v52, v55, v54
	v_fmac_f32_e32 v55, v56, v53
	v_fma_f32 v52, -v52, v55, v54
	v_div_fmas_f32 v52, v52, v53, v55
	v_div_fixup_f32 v46, v52, v46, 1.0
	v_mul_f32_e32 v46, v46, v48
	v_fmac_f32_e32 v31, v6, v46
	v_fmac_f32_e32 v32, v39, v46
	v_fmac_f32_e32 v33, v40, v46
	v_fmac_f32_e32 v34, v41, v46
	v_fmac_f32_e32 v35, v42, v46
	v_fmac_f32_e32 v36, v43, v46
	v_fmac_f32_e32 v37, v44, v46
	v_fmac_f32_e32 v38, v45, v46
	v_fmac_f32_e32 v7, v47, v46
	v_lshl_add_u64 v[100:101], v[50:51], 0, s[100:101]
	global_load_ushort v46, v[50:51], off offset:1024
	global_load_ushort v102, v[100:101], off offset:1024
	s_waitcnt vmcnt(1)
	v_lshlrev_b32_e32 v46, 16, v46
	v_mul_f32_e32 v46, 0xbfb8aa3b, v46
	v_exp_f32_e32 v46, v46
	s_nop 0
	v_add_f32_e32 v46, 1.0, v46
	v_div_scale_f32 v47, s[72:73], v46, v46, 1.0
	v_rcp_f32_e32 v48, v47
	s_nop 0
	v_fma_f32 v49, -v47, v48, 1.0
	v_fmac_f32_e32 v48, v49, v48
	v_div_scale_f32 v49, vcc, 1.0, v46, 1.0
	v_mul_f32_e32 v52, v49, v48
	v_fma_f32 v53, -v47, v52, v49
	v_fmac_f32_e32 v52, v53, v48
	v_fma_f32 v47, -v47, v52, v49
	v_div_fmas_f32 v47, v47, v48, v52
	v_div_fixup_f32 v46, v47, v46, 1.0
	v_lshl_add_u64 v[100:101], v[50:51], 0, s[100:101]
	global_load_ushort v47, v[50:51], off
	global_load_ushort v102, v[100:101], off
	s_waitcnt vmcnt(1)
; __device__ __forceinline__ float bf2f(bfu h) { return __uint_as_float(((unsigned)h) << 16); }
; __device__ __forceinline__ float sigm(float x) { return 1.f / (1.f + __expf(-x)); }
;   __device__ __forceinline__ bfu* glu() const { return (bfu*)(b + L::o_glu); }
; template <int G>
; __device__ __forceinline__ void p2_conformer(const Params& P, const Ptrs<G>& w, int layer, int item, float* cv, int kslot) {
;     ...
;     for (int sr = 0; sr < 62; ++sr) {
;       const int s = t0 - 30 + sr;
;       float h0 = 0.f;
;       if (s >= 0) {
;         const bfu* gp = w.glu() + (seqbase + s) * 1024 + c;
;         h0 = bf2f(gp[0]) * sigm(bf2f(gp[512]));
;       }
; #pragma unroll
;       for (int tr = 0; tr < 32; ++tr) {
;         const int j = sr - tr;
;         if (j >= 0 && j <= 30) a[tr] += wj[j] * h0;
;       }
;     }
	v_lshlrev_b32_e32 v47, 16, v47
	v_mul_f32_e32 v46, v46, v47
	v_fmac_f32_e32 v7, v45, v46
	v_lshl_add_u64 v[100:101], v[50:51], 0, s[100:101]
	global_load_ushort v45, v[50:51], off offset:3072
	global_load_ushort v102, v[100:101], off offset:3072
	v_fmac_f32_e32 v32, v6, v46
	v_fmac_f32_e32 v33, v39, v46
	v_fmac_f32_e32 v34, v40, v46
	v_fmac_f32_e32 v35, v41, v46
	v_fmac_f32_e32 v36, v42, v46
	v_fmac_f32_e32 v37, v43, v46
	v_fmac_f32_e32 v38, v44, v46
	s_waitcnt vmcnt(1)
	v_lshlrev_b32_e32 v45, 16, v45
	v_mul_f32_e32 v45, 0xbfb8aa3b, v45
	v_exp_f32_e32 v45, v45
	s_nop 0
	v_add_f32_e32 v45, 1.0, v45
	v_div_scale_f32 v46, s[72:73], v45, v45, 1.0
	v_rcp_f32_e32 v47, v46
	s_mov_b32 s72, 0xd000
	v_fma_f32 v48, -v46, v47, 1.0
	v_fmac_f32_e32 v47, v48, v47
	v_div_scale_f32 v48, vcc, 1.0, v45, 1.0
	v_mul_f32_e32 v49, v48, v47
	v_fma_f32 v52, -v46, v49, v48
	v_fmac_f32_e32 v49, v52, v47
	v_fma_f32 v46, -v46, v49, v48
	v_div_fmas_f32 v46, v46, v47, v49
	v_div_fixup_f32 v45, v46, v45, 1.0
	v_lshl_add_u64 v[100:101], v[50:51], 0, s[100:101]
	global_load_ushort v46, v[50:51], off offset:2048
	global_load_ushort v102, v[100:101], off offset:2048
	s_waitcnt vmcnt(1)
	v_lshlrev_b32_e32 v46, 16, v46
	v_mul_f32_e32 v45, v45, v46
	v_fmac_f32_e32 v7, v44, v45
	v_add_co_u32_e32 v44, vcc, s72, v4
	v_fmac_f32_e32 v33, v6, v45
	v_fmac_f32_e32 v34, v39, v45
	v_fmac_f32_e32 v35, v40, v45
	v_fmac_f32_e32 v36, v41, v45
	v_fmac_f32_e32 v37, v42, v45
	v_fmac_f32_e32 v38, v43, v45
	v_addc_co_u32_e32 v45, vcc, 0, v5, vcc
	v_lshl_add_u64 v[100:101], v[44:45], 0, s[100:101]
	global_load_ushort v46, v[44:45], off offset:1024
	global_load_ushort v102, v[100:101], off offset:1024
	s_waitcnt vmcnt(1)
	v_lshlrev_b32_e32 v46, 16, v46
	v_mul_f32_e32 v46, 0xbfb8aa3b, v46
	v_exp_f32_e32 v46, v46
	s_nop 0
	v_add_f32_e32 v46, 1.0, v46
	v_div_scale_f32 v47, s[72:73], v46, v46, 1.0
	v_rcp_f32_e32 v48, v47
	s_mov_b32 s72, 0xe000
	v_fma_f32 v49, -v47, v48, 1.0
	v_fmac_f32_e32 v48, v49, v48
	v_div_scale_f32 v49, vcc, 1.0, v46, 1.0
	v_mul_f32_e32 v50, v49, v48
	v_fma_f32 v51, -v47, v50, v49
	v_fmac_f32_e32 v50, v51, v48
	v_fma_f32 v47, -v47, v50, v49
	v_div_fmas_f32 v47, v47, v48, v50
	v_div_fixup_f32 v48, v47, v46, 1.0
	v_add_co_u32_e32 v46, vcc, s72, v4
	s_nop 1
	v_addc_co_u32_e32 v47, vcc, 0, v5, vcc
	v_lshl_add_u64 v[100:101], v[46:47], 0, s[100:101]
	global_load_ushort v49, v[46:47], off offset:-4096
	global_load_ushort v102, v[100:101], off offset:-4096
	s_waitcnt vmcnt(1)
	v_lshlrev_b32_e32 v49, 16, v49
	v_mul_f32_e32 v48, v48, v49
	v_fmac_f32_e32 v7, v43, v48
	v_lshl_add_u64 v[100:101], v[44:45], 0, s[100:101]
	global_load_ushort v43, v[44:45], off offset:3072
	global_load_ushort v102, v[100:101], off offset:3072
	v_fmac_f32_e32 v34, v6, v48
	v_lshl_add_u64 v[100:101], v[44:45], 0, s[100:101]
	global_load_ushort v44, v[44:45], off offset:2048
	global_load_ushort v102, v[100:101], off offset:2048
	v_fmac_f32_e32 v35, v39, v48
	v_fmac_f32_e32 v36, v40, v48
	v_fmac_f32_e32 v37, v41, v48
	v_fmac_f32_e32 v38, v42, v48
	s_waitcnt vmcnt(3)
	v_lshlrev_b32_e32 v43, 16, v43
	v_mul_f32_e32 v43, 0xbfb8aa3b, v43
	v_exp_f32_e32 v43, v43
	s_waitcnt vmcnt(1)
	v_lshlrev_b32_e32 v44, 16, v44
	v_add_f32_e32 v43, 1.0, v43
	v_div_scale_f32 v48, s[72:73], v43, v43, 1.0
	v_rcp_f32_e32 v49, v48
	s_nop 0
	v_fma_f32 v50, -v48, v49, 1.0
	v_fmac_f32_e32 v49, v50, v49
	v_div_scale_f32 v50, vcc, 1.0, v43, 1.0
	v_mul_f32_e32 v51, v50, v49
	v_fma_f32 v52, -v48, v51, v50
	v_fmac_f32_e32 v51, v52, v49
	v_fma_f32 v48, -v48, v51, v50
	v_div_fmas_f32 v48, v48, v49, v51
	v_div_fixup_f32 v43, v48, v43, 1.0
	v_mul_f32_e32 v43, v43, v44
	v_fmac_f32_e32 v7, v42, v43
	v_lshl_add_u64 v[100:101], v[46:47], 0, s[100:101]
	global_load_ushort v42, v[46:47], off offset:1024
	global_load_ushort v102, v[100:101], off offset:1024
	v_fmac_f32_e32 v35, v6, v43
	v_fmac_f32_e32 v36, v39, v43
	v_fmac_f32_e32 v37, v40, v43
	v_fmac_f32_e32 v38, v41, v43
	s_waitcnt vmcnt(1)
	v_lshlrev_b32_e32 v42, 16, v42
	v_mul_f32_e32 v42, 0xbfb8aa3b, v42
	v_exp_f32_e32 v42, v42
	s_nop 0
	v_add_f32_e32 v42, 1.0, v42
	v_div_scale_f32 v43, s[72:73], v42, v42, 1.0
	v_rcp_f32_e32 v44, v43
	s_nop 0
	v_fma_f32 v45, -v43, v44, 1.0
	v_fmac_f32_e32 v44, v45, v44
	v_div_scale_f32 v45, vcc, 1.0, v42, 1.0
	v_mul_f32_e32 v48, v45, v44
	v_fma_f32 v49, -v43, v48, v45
	v_fmac_f32_e32 v48, v49, v44
	v_fma_f32 v43, -v43, v48, v45
	v_div_fmas_f32 v43, v43, v44, v48
	v_div_fixup_f32 v42, v43, v42, 1.0
	v_lshl_add_u64 v[100:101], v[46:47], 0, s[100:101]
	global_load_ushort v43, v[46:47], off
	global_load_ushort v102, v[100:101], off
	s_waitcnt vmcnt(1)
; __device__ __forceinline__ float bf2f(bfu h) { return __uint_as_float(((unsigned)h) << 16); }
; __device__ __forceinline__ float sigm(float x) { return 1.f / (1.f + __expf(-x)); }
;   __device__ __forceinline__ bfu* glu() const { return (bfu*)(b + L::o_glu); }
; template <int G>
; __device__ __forceinline__ void p2_conformer(const Params& P, const Ptrs<G>& w, int layer, int item, float* cv, int kslot) {
;     ...
;     for (int sr = 0; sr < 62; ++sr) {
;       const int s = t0 - 30 + sr;
;       float h0 = 0.f;
;       if (s >= 0) {
;         const bfu* gp = w.glu() + (seqbase + s) * 1024 + c;
;         h0 = bf2f(gp[0]) * sigm(bf2f(gp[512]));
;       }
; #pragma unroll
;       for (int tr = 0; tr < 32; ++tr) {
;         const int j = sr - tr;
;         if (j >= 0 && j <= 30) a[tr] += wj[j] * h0;
;       }
;     }
; #pragma unroll
;     for (int tr = 0; tr < 32; ++tr) cv[tr * 512 + c] = a[tr];
	v_lshlrev_b32_e32 v43, 16, v43
	v_mul_f32_e32 v42, v42, v43
	v_fmac_f32_e32 v7, v41, v42
	v_lshl_add_u64 v[100:101], v[46:47], 0, s[100:101]
	global_load_ushort v41, v[46:47], off offset:3072
	global_load_ushort v102, v[100:101], off offset:3072
	v_fmac_f32_e32 v36, v6, v42
	v_fmac_f32_e32 v37, v39, v42
	v_fmac_f32_e32 v38, v40, v42
	s_waitcnt vmcnt(1)
	v_lshlrev_b32_e32 v41, 16, v41
	v_mul_f32_e32 v41, 0xbfb8aa3b, v41
	v_exp_f32_e32 v41, v41
	s_nop 0
	v_add_f32_e32 v41, 1.0, v41
	v_div_scale_f32 v42, s[72:73], v41, v41, 1.0
	v_rcp_f32_e32 v43, v42
	s_nop 0
	v_fma_f32 v44, -v42, v43, 1.0
	v_fmac_f32_e32 v43, v44, v43
	v_div_scale_f32 v44, vcc, 1.0, v41, 1.0
	v_mul_f32_e32 v45, v44, v43
	v_fma_f32 v48, -v42, v45, v44
	v_fmac_f32_e32 v45, v48, v43
	v_fma_f32 v42, -v42, v45, v44
	v_div_fmas_f32 v42, v42, v43, v45
	v_div_fixup_f32 v41, v42, v41, 1.0
	v_lshl_add_u64 v[100:101], v[46:47], 0, s[100:101]
	global_load_ushort v42, v[46:47], off offset:2048
	global_load_ushort v102, v[100:101], off offset:2048
	v_add_co_u32_e32 v4, vcc, s92, v4
	s_mov_b64 s[92:93], 0
	s_nop 0
	v_addc_co_u32_e32 v5, vcc, 0, v5, vcc
	s_waitcnt vmcnt(1)
	v_lshlrev_b32_e32 v42, 16, v42
	v_mul_f32_e32 v41, v41, v42
	v_fmac_f32_e32 v7, v40, v41
	v_lshl_add_u64 v[100:101], v[4:5], 0, s[100:101]
	global_load_ushort v40, v[4:5], off offset:1024
	global_load_ushort v102, v[100:101], off offset:1024
	v_fmac_f32_e32 v37, v6, v41
	v_fmac_f32_e32 v38, v39, v41
	s_waitcnt vmcnt(1)
	v_lshlrev_b32_e32 v40, 16, v40
	v_mul_f32_e32 v40, 0xbfb8aa3b, v40
	v_exp_f32_e32 v40, v40
	s_nop 0
	v_add_f32_e32 v40, 1.0, v40
	v_div_scale_f32 v41, s[72:73], v40, v40, 1.0
	v_rcp_f32_e32 v42, v41
	s_nop 0
	v_fma_f32 v43, -v41, v42, 1.0
	v_fmac_f32_e32 v42, v43, v42
	v_div_scale_f32 v43, vcc, 1.0, v40, 1.0
	v_mul_f32_e32 v44, v43, v42
	v_fma_f32 v45, -v41, v44, v43
	v_fmac_f32_e32 v44, v45, v42
	v_fma_f32 v41, -v41, v44, v43
	v_div_fmas_f32 v41, v41, v42, v44
	v_div_fixup_f32 v40, v41, v40, 1.0
	v_lshl_add_u64 v[100:101], v[4:5], 0, s[100:101]
	global_load_ushort v41, v[4:5], off
	global_load_ushort v102, v[100:101], off
	s_waitcnt vmcnt(1)
	v_lshlrev_b32_e32 v41, 16, v41
	v_mul_f32_e32 v40, v40, v41
	v_fmac_f32_e32 v7, v39, v40
	v_lshl_add_u64 v[100:101], v[4:5], 0, s[100:101]
	global_load_ushort v39, v[4:5], off offset:3072
	global_load_ushort v102, v[100:101], off offset:3072
	v_fmac_f32_e32 v38, v6, v40
	v_lshl_add_u64 v[100:101], v[4:5], 0, s[100:101]
	global_load_ushort v4, v[4:5], off offset:2048
	global_load_ushort v102, v[100:101], off offset:2048
	s_waitcnt vmcnt(3)
	v_lshlrev_b32_e32 v39, 16, v39
	v_mul_f32_e32 v39, 0xbfb8aa3b, v39
	v_exp_f32_e32 v39, v39
	s_waitcnt vmcnt(1)
	v_lshlrev_b32_e32 v4, 16, v4
	v_add_f32_e32 v39, 1.0, v39
	v_div_scale_f32 v40, s[72:73], v39, v39, 1.0
	v_rcp_f32_e32 v41, v40
	s_movk_i32 s72, 0x100
	v_fma_f32 v42, -v40, v41, 1.0
	v_fmac_f32_e32 v41, v42, v41
	v_div_scale_f32 v42, vcc, 1.0, v39, 1.0
	v_mul_f32_e32 v43, v42, v41
	v_fma_f32 v44, -v40, v43, v42
	v_fmac_f32_e32 v43, v44, v41
	v_fma_f32 v40, -v40, v43, v42
	v_div_fmas_f32 v40, v40, v41, v43
	v_div_fixup_f32 v39, v40, v39, 1.0
	v_mul_f32_e32 v4, v39, v4
	s_and_b64 vcc, exec, s[10:11]
	v_fmac_f32_e32 v7, v6, v4
	ds_write2st64_b32 v2, v3, v8 offset1:8
	ds_write2st64_b32 v2, v9, v10 offset0:16 offset1:24
	ds_write2st64_b32 v2, v11, v12 offset0:32 offset1:40
	ds_write2st64_b32 v2, v13, v14 offset0:48 offset1:56
	ds_write2st64_b32 v2, v15, v17 offset0:64 offset1:72
	ds_write2st64_b32 v2, v18, v19 offset0:80 offset1:88
	ds_write2st64_b32 v2, v20, v21 offset0:96 offset1:104
	ds_write2st64_b32 v2, v22, v23 offset0:112 offset1:120
	ds_write2st64_b32 v2, v24, v25 offset0:128 offset1:136
	ds_write2st64_b32 v2, v26, v27 offset0:144 offset1:152
	ds_write2st64_b32 v2, v28, v29 offset0:160 offset1:168
	ds_write2st64_b32 v2, v30, v31 offset0:176 offset1:184
	ds_write2st64_b32 v2, v32, v33 offset0:192 offset1:200
	ds_write2st64_b32 v2, v34, v35 offset0:208 offset1:216
	ds_write2st64_b32 v2, v36, v37 offset0:224 offset1:232
	ds_write2st64_b32 v2, v38, v7 offset0:240 offset1:248
	s_cbranch_vccnz .LBB0_409

; template <int G>
; __global__ void __launch_bounds__(256, 2) fwd_kernel(Params P) {
	.amdhsa_kernel _Z10fwd_kernelILi2EEv6Params
		.amdhsa_group_segment_fixed_size 73748
		.amdhsa_private_segment_fixed_size 0
		.amdhsa_kernarg_size 432
		.amdhsa_user_sgpr_count 2
		.amdhsa_user_sgpr_dispatch_ptr 0
		.amdhsa_user_sgpr_queue_ptr 0
		.amdhsa_user_sgpr_kernarg_segment_ptr 1
		.amdhsa_user_sgpr_dispatch_id 0
		.amdhsa_user_sgpr_kernarg_preload_length 0
		.amdhsa_user_sgpr_kernarg_preload_offset 0
		.amdhsa_user_sgpr_private_segment_size 0
		.amdhsa_uses_dynamic_stack 0
		.amdhsa_enable_private_segment 0
		.amdhsa_system_sgpr_workgroup_id_x 1
		.amdhsa_system_sgpr_workgroup_id_y 0
		.amdhsa_system_sgpr_workgroup_id_z 0
		.amdhsa_system_sgpr_workgroup_info 0
		.amdhsa_system_vgpr_workitem_id 2
		.amdhsa_next_free_vgpr 256
		.amdhsa_next_free_sgpr 102
		.amdhsa_accum_offset 256
		.amdhsa_reserve_vcc 1
		.amdhsa_float_round_mode_32 0
		.amdhsa_float_round_mode_16_64 0
		.amdhsa_float_denorm_mode_32 3
		.amdhsa_float_denorm_mode_16_64 3
		.amdhsa_dx10_clamp 1
		.amdhsa_ieee_mode 1
		.amdhsa_fp16_overflow 0
		.amdhsa_tg_split 0
		.amdhsa_exception_fp_ieee_invalid_op 0
		.amdhsa_exception_fp_denorm_src 0
		.amdhsa_exception_fp_ieee_div_zero 0
		.amdhsa_exception_fp_ieee_overflow 0
		.amdhsa_exception_fp_ieee_underflow 0
		.amdhsa_exception_fp_ieee_inexact 0
		.amdhsa_exception_int_div_zero 0
	.end_amdhsa_kernel

; template <int G>
; __global__ void __launch_bounds__(256, 2) fwd_kernel(Params P) {
amdhsa.kernels:
  - .agpr_count:     0
    .args:
      - .offset:         0
        .size:           176
        .value_kind:     by_value
      - .offset:         176
        .size:           4
        .value_kind:     hidden_block_count_x
      - .offset:         180
        .size:           4
        .value_kind:     hidden_block_count_y
      - .offset:         184
        .size:           4
        .value_kind:     hidden_block_count_z
      - .offset:         188
        .size:           2
        .value_kind:     hidden_group_size_x
      - .offset:         190
        .size:           2
        .value_kind:     hidden_group_size_y
      - .offset:         192
        .size:           2
        .value_kind:     hidden_group_size_z
      - .offset:         194
        .size:           2
        .value_kind:     hidden_remainder_x
      - .offset:         196
        .size:           2
        .value_kind:     hidden_remainder_y
      - .offset:         198
        .size:           2
        .value_kind:     hidden_remainder_z
      - .offset:         216
        .size:           8
        .value_kind:     hidden_global_offset_x
      - .offset:         224
        .size:           8
        .value_kind:     hidden_global_offset_y
      - .offset:         232
        .size:           8
        .value_kind:     hidden_global_offset_z
      - .offset:         240
        .size:           2
        .value_kind:     hidden_grid_dims
      - .offset:         264
        .size:           8
        .value_kind:     hidden_multigrid_sync_arg
    .group_segment_fixed_size: 73748
    .kernarg_segment_align: 8
    .kernarg_segment_size: 432
    .language:       OpenCL C
    .language_version:
      - 2
      - 0
    .max_flat_workgroup_size: 256
    .name:           _Z10fwd_kernelILi2EEv6Params
    .private_segment_fixed_size: 0
    .sgpr_count:     108
    .sgpr_spill_count: 210
    .symbol:         _Z10fwd_kernelILi2EEv6Params.kd
    .uniform_work_group_size: 1
    .uses_dynamic_stack: false
    .vgpr_count:     256
    .vgpr_spill_count: 0
    .wavefront_size: 64
